# attn loop: per-tile barrier moved before the last PV MFMA group; next tile's first K fragments are read under those MFMAs (no exposed LDS latency after the barrier)
# baseline (speedup 1.0000x reference)
; __device__ __forceinline__ void finishSM(f32x16& p0, f32x16& p1, float alpha, float& l_reg, bf16x8& pa0, bf16x8& pa1, bf16x8& pa2, bf16x8& pa3) {
; #pragma unroll
;   for (int r = 0; r < 16; ++r) p1[r] = __builtin_amdgcn_exp2f(p1[r]);
;   float ps = 0;
; #pragma unroll
;   for (int r = 0; r < 16; ++r) ps += p0[r];
; #pragma unroll
;   for (int r = 0; r < 16; ++r) ps += p1[r];
;   { auto rr = __builtin_amdgcn_permlane32_swap(__float_as_uint(ps), __float_as_uint(ps), false, false);
;     ps = __uint_as_float(rr[0]) + __uint_as_float(rr[1]); }
;   l_reg = l_reg * alpha + ps;
;     ...
;   PK4(p0, 0, pa0); PK4(p0, 8, pa1); PK4(p1, 0, pa2); PK4(p1, 8, pa3);
;     ...
; }
; __device__ __forceinline__ void qkt(f32x16& p0, f32x16& p1, const char* Ks, const bf16x8* qr, const char* qrl, int r32, int hi) {
;   p0 = f32x16{}; p1 = f32x16{};
; #pragma unroll
;   for (int d0 = 0; d0 < 8; ++d0) { int cb = (d0 * 16 + hi * 8) * 2;
;     bf16x8 b0 = *reinterpret_cast<const bf16x8*>(Ks + KSWZ(r32, cb));
;     bf16x8 b1 = *reinterpret_cast<const bf16x8*>(Ks + KSWZ(32 + r32, cb));
;     p0 = __builtin_amdgcn_mfma_f32_32x32x16_bf16(b0, qr[d0], p0, 0, 0, 0);
;     p1 = __builtin_amdgcn_mfma_f32_32x32x16_bf16(b1, qr[d0], p1, 0, 0, 0); }
; #pragma unroll
;   for (int d0 = 8; d0 < 12; ++d0) { int cb = (d0 * 16 + hi * 8) * 2;
;     bf16x8 b0 = *reinterpret_cast<const bf16x8*>(Ks + KSWZ(r32, cb));
;     bf16x8 b1 = *reinterpret_cast<const bf16x8*>(Ks + KSWZ(32 + r32, cb));
;     bf16x8 qf = *reinterpret_cast<const bf16x8*>(qrl + (((2 * (d0 - 8) + hi) ^ ((r32 >> 1) & 7)) << 4));
;     p0 = __builtin_amdgcn_mfma_f32_32x32x16_bf16(b0, qf, p0, 0, 0, 0);
;     p1 = __builtin_amdgcn_mfma_f32_32x32x16_bf16(b1, qf, p1, 0, 0, 0); }
; }
.LBB0_1151:
	s_sub_i32 s30, s76, 1
	s_cmp_eq_u32 s76, 0
	s_cselect_b32 s30, 2, s30
	s_add_i32 s18, s76, 1
	s_cmp_lg_u32 s76, 2
	s_cselect_b32 s18, s18, 0
	ds_read_b128 v[232:235], v199 offset:36864
	ds_read_b128 v[236:239], v199 offset:49152
	ds_read_b128 v[240:243], v205 offset:36864
	ds_read_b128 v[248:251], v205 offset:49152
	v_exp_f32_e32 v162, v162
	v_add_f32_e32 v211, v225, v228
	v_exp_f32_e32 v163, v163
	v_add_f32_e32 v211, v226, v211
	v_exp_f32_e32 v160, v160
	s_waitcnt lgkmcnt(2)
	v_mfma_f32_32x32x16_bf16 v[80:95], v[232:235], v[124:127], 0
	ds_read_b128 v[232:235], v206 offset:36864
	v_add_f32_e32 v211, v229, v211
	v_exp_f32_e32 v161, v161
	v_add_f32_e32 v211, v227, v211
	v_exp_f32_e32 v158, v158
	v_mfma_f32_32x32x16_bf16 v[64:79], v[236:239], v[124:127], 0
	ds_read_b128 v[236:239], v206 offset:49152
	v_add_f32_e32 v211, v230, v211
	v_exp_f32_e32 v159, v159
	v_add_f32_e32 v211, v223, v211
	v_exp_f32_e32 v156, v156
	s_waitcnt lgkmcnt(2)
	v_mfma_f32_32x32x16_bf16 v[80:95], v[240:243], v[120:123], v[80:95]
	ds_read_b128 v[240:243], v208 offset:36864
	v_add_f32_e32 v211, v224, v211
	v_exp_f32_e32 v157, v157
	v_add_f32_e32 v211, v219, v211
	v_exp_f32_e32 v154, v154
	v_mfma_f32_32x32x16_bf16 v[64:79], v[248:251], v[120:123], v[64:79]
	ds_read_b128 v[248:251], v208 offset:49152
	v_add_f32_e32 v211, v221, v211
	v_exp_f32_e32 v155, v155
	v_add_f32_e32 v211, v220, v211
	v_exp_f32_e32 v152, v152
	s_waitcnt lgkmcnt(2)
	v_mfma_f32_32x32x16_bf16 v[80:95], v[232:235], v[116:119], v[80:95]
	ds_read_b128 v[232:235], v207 offset:36864
	v_add_f32_e32 v211, v222, v211
	v_exp_f32_e32 v153, v153
	v_add_f32_e32 v211, v215, v211
	v_exp_f32_e32 v150, v150
	v_mfma_f32_32x32x16_bf16 v[64:79], v[236:239], v[116:119], v[64:79]
	ds_read_b128 v[236:239], v207 offset:49152
	v_add_f32_e32 v211, v217, v211
	v_exp_f32_e32 v151, v151
	v_add_f32_e32 v211, v216, v211
	v_exp_f32_e32 v148, v148
	s_waitcnt lgkmcnt(2)
	v_mfma_f32_32x32x16_bf16 v[80:95], v[240:243], v[112:115], v[80:95]
	ds_read_b128 v[240:243], v204 offset:36864
	v_add_f32_e32 v211, v218, v211
	v_exp_f32_e32 v149, v149
	v_add_f32_e32 v212, v162, v163
	v_add_f32_e32 v212, v160, v212
	v_add_f32_e32 v212, v161, v212
	v_mfma_f32_32x32x16_bf16 v[64:79], v[248:251], v[112:115], v[64:79]
	ds_read_b128 v[248:251], v204 offset:49152
	v_add_f32_e32 v212, v158, v212
	v_add_f32_e32 v212, v159, v212
	v_add_f32_e32 v212, v156, v212
	v_add_f32_e32 v212, v157, v212
	v_add_f32_e32 v212, v154, v212
	v_add_f32_e32 v212, v155, v212
	s_waitcnt lgkmcnt(2)
	v_mfma_f32_32x32x16_bf16 v[80:95], v[232:235], v[108:111], v[80:95]
	ds_read_b128 v[232:235], v203 offset:36864
	v_add_f32_e32 v212, v152, v212
	v_add_f32_e32 v212, v153, v212
	v_add_f32_e32 v212, v150, v212
	v_add_f32_e32 v212, v151, v212
	v_add_f32_e32 v212, v148, v212
	v_add_f32_e32 v212, v149, v212
	v_mfma_f32_32x32x16_bf16 v[64:79], v[236:239], v[108:111], v[64:79]
	ds_read_b128 v[236:239], v203 offset:49152
	v_add_f32_e32 v211, v211, v212
	v_mov_b32_e32 v212, v211
	s_lshl_b32 s19, s18, 14
	v_add_u32_e32 v231, s19, v183
	s_waitcnt vmcnt(0)
	ds_write_b128 v231, v[140:143]
	v_add_u32_e32 v140, s19, v184
	ds_write_b128 v140, v[144:147]
	ds_write_b128 v185, v[136:139] offset:12288
	s_waitcnt lgkmcnt(5)
	v_mfma_f32_32x32x16_bf16 v[80:95], v[240:243], v[104:107], v[80:95]
	ds_read_b128 v[240:243], v200 offset:36864
	ds_write_b128 v185, v[132:135] offset:24576
	s_mov_b32 s18, 0xfffa0000
	ds_write_b128 v186, v[128:131] offset:12288
	v_add_co_u32_e32 v128, vcc, s18, v168
	s_mov_b32 s18, 0xfffc0000
	s_nop 0
	v_addc_co_u32_e32 v129, vcc, -1, v169, vcc
	v_add_co_u32_e32 v130, vcc, s18, v168
	s_movk_i32 s18, 0xe000
	s_nop 0
	v_addc_co_u32_e32 v131, vcc, -1, v169, vcc
	v_mfma_f32_32x32x16_bf16 v[64:79], v[248:251], v[104:107], v[64:79]
	ds_read_b128 v[248:251], v200 offset:49152
	global_load_dwordx4 v[140:143], v[128:129], off
	global_load_dwordx4 v[136:139], v[128:129], off offset:-256
	global_load_dwordx4 v[144:147], v[130:131], off
	global_load_dwordx4 v[132:135], v[130:131], off offset:-256
	v_add_co_u32_e32 v128, vcc, s18, v166
	s_nop 1
	v_addc_co_u32_e32 v129, vcc, -1, v167, vcc
	s_waitcnt lgkmcnt(7)
; __device__ __forceinline__ void qkt(f32x16& p0, f32x16& p1, const char* Ks, const bf16x8* qr, const char* qrl, int r32, int hi) {
;   p0 = f32x16{}; p1 = f32x16{};
; #pragma unroll
;   for (int d0 = 0; d0 < 8; ++d0) { int cb = (d0 * 16 + hi * 8) * 2;
;     bf16x8 b0 = *reinterpret_cast<const bf16x8*>(Ks + KSWZ(r32, cb));
;     bf16x8 b1 = *reinterpret_cast<const bf16x8*>(Ks + KSWZ(32 + r32, cb));
;     p0 = __builtin_amdgcn_mfma_f32_32x32x16_bf16(b0, qr[d0], p0, 0, 0, 0);
;     p1 = __builtin_amdgcn_mfma_f32_32x32x16_bf16(b1, qr[d0], p1, 0, 0, 0); }
; #pragma unroll
;   for (int d0 = 8; d0 < 12; ++d0) { int cb = (d0 * 16 + hi * 8) * 2;
;     bf16x8 b0 = *reinterpret_cast<const bf16x8*>(Ks + KSWZ(r32, cb));
;     bf16x8 b1 = *reinterpret_cast<const bf16x8*>(Ks + KSWZ(32 + r32, cb));
;     bf16x8 qf = *reinterpret_cast<const bf16x8*>(qrl + (((2 * (d0 - 8) + hi) ^ ((r32 >> 1) & 7)) << 4));
;     p0 = __builtin_amdgcn_mfma_f32_32x32x16_bf16(b0, qf, p0, 0, 0, 0);
;     p1 = __builtin_amdgcn_mfma_f32_32x32x16_bf16(b1, qf, p1, 0, 0, 0); }
; }
; __device__ __forceinline__ int v_st(int k, int c) { const int kk = (k & ~0xC) | ((k & 4) << 1) | ((k & 8) >> 1); return ((kk >> 3) * 4 + (c >> 5)) * 512 + ((kk & 7) * 32 + (c & 31)) * 2; }
; __device__ __forceinline__ int v_rd_base(int lane) { return ((lane & 3) << 3) | (((lane >> 2) & 3) << 6) | (((lane >> 4) & 1) << 5) | (((lane >> 5) & 1) << 8); }
; template <int OFF> __device__ __forceinline__ s16x4 tr_read(int vb) {
;   s16x4 r; asm volatile("ds_read_b64_tr_b16 %0, %1 offset:%2" : "=&v"(r) : "v"(vb), "i"(OFF) : "memory"); return r;
; }
; template <int D0> __device__ __forceinline__ void pv_one(f32x16& od, int vb, bf16x8 pa0, bf16x8 pa1, bf16x8 pa2, bf16x8 pa3) {
;   const s16x4 l0 = tr_read<v_rd_off(D0, 0, 0)>(vb), h0 = tr_read<v_rd_off(D0, 0, 1)>(vb), l1 = tr_read<v_rd_off(D0, 1, 0)>(vb), h1 = tr_read<v_rd_off(D0, 1, 1)>(vb);
;   const s16x4 l2 = tr_read<v_rd_off(D0, 2, 0)>(vb), h2 = tr_read<v_rd_off(D0, 2, 1)>(vb), l3 = tr_read<v_rd_off(D0, 3, 0)>(vb), h3 = tr_read<v_rd_off(D0, 3, 1)>(vb);
;   asm volatile("s_waitcnt lgkmcnt(0)" ::: "memory"); SBAR();
;     ...
;   od = __builtin_amdgcn_mfma_f32_32x32x16_bf16(pa0, PK(l0, h0), od, 0, 0, 0);
;   od = __builtin_amdgcn_mfma_f32_32x32x16_bf16(pa1, PK(l1, h1), od, 0, 0, 0);
;   od = __builtin_amdgcn_mfma_f32_32x32x16_bf16(pa2, PK(l2, h2), od, 0, 0, 0);
	v_mfma_f32_32x32x16_bf16 v[80:95], v[232:235], v[100:103], v[80:95]
	ds_read_b128 v[232:235], v191 offset:36864
	global_load_dwordx4 v[128:131], v[128:129], off
	v_cvt_pk_bf16_f32 v158, v158, v159
	v_cvt_pk_bf16_f32 v159, v156, v157
	v_permlane32_swap_b32_e32 v211, v212
	v_cvt_pk_bf16_f32 v156, v162, v163
	v_cvt_pk_bf16_f32 v157, v160, v161
	v_mfma_f32_32x32x16_bf16 v[64:79], v[236:239], v[100:103], v[64:79]
	ds_read_b128 v[236:239], v202 offset:49152
	v_cvt_pk_bf16_f32 v160, v154, v155
	v_cvt_pk_bf16_f32 v161, v152, v153
	v_cvt_pk_bf16_f32 v162, v150, v151
	v_cvt_pk_bf16_f32 v163, v148, v149
	v_add_f32_e32 v211, v211, v212
	v_cvt_pk_bf16_f32 v148, v225, v228
	s_waitcnt lgkmcnt(2)
	v_mfma_f32_32x32x16_bf16 v[80:95], v[240:243], v[96:99], v[80:95]
	ds_read_b128 v[240:243], v182
	v_cvt_pk_bf16_f32 v149, v226, v229
	v_cvt_pk_bf16_f32 v150, v227, v230
	v_cvt_pk_bf16_f32 v151, v223, v224
	v_cvt_pk_bf16_f32 v152, v219, v221
	v_cvt_pk_bf16_f32 v153, v220, v222
	v_cvt_pk_bf16_f32 v154, v215, v217
	v_mfma_f32_32x32x16_bf16 v[64:79], v[248:251], v[96:99], v[64:79]
	ds_read_b128 v[248:251], v198 offset:36864
	v_cvt_pk_bf16_f32 v155, v216, v218
	v_fma_f32 v176, v209, v176, v211
	s_waitcnt lgkmcnt(1)
	v_mfma_f32_32x32x16_bf16 v[80:95], v[232:235], v[240:243], v[80:95]
	ds_read_b128 v[232:235], v201 offset:49152
	v_mfma_f32_32x32x16_bf16 v[64:79], v[236:239], v[240:243], v[64:79]
	ds_read_b128 v[236:239], v181
	ds_read_b128 v[240:243], v187 offset:36864
	s_waitcnt lgkmcnt(1)
	v_mfma_f32_32x32x16_bf16 v[80:95], v[248:251], v[236:239], v[80:95]
	ds_read_b128 v[248:251], v189 offset:49152
	v_mfma_f32_32x32x16_bf16 v[64:79], v[232:235], v[236:239], v[64:79]
	ds_read_b128 v[232:235], v179
	ds_read_b128 v[236:239], v188 offset:36864
	s_waitcnt lgkmcnt(1)
	v_mfma_f32_32x32x16_bf16 v[80:95], v[240:243], v[232:235], v[80:95]
	ds_read_b128 v[240:243], v190 offset:49152
	v_mfma_f32_32x32x16_bf16 v[64:79], v[248:251], v[232:235], v[64:79]
	ds_read_b128 v[248:251], v177
	s_waitcnt lgkmcnt(0)
	v_mfma_f32_32x32x16_bf16 v[80:95], v[236:239], v[248:251], v[80:95]
	v_mfma_f32_32x32x16_bf16 v[64:79], v[240:243], v[248:251], v[64:79]
	s_lshl_b32 s31, s30, 14
	v_add_u32_e32 v180, s31, v178
	ds_read_b64_tr_b16 v[232:233], v180 offset:0
	ds_read_b64_tr_b16 v[234:235], v180 offset:2048
	ds_read_b64_tr_b16 v[236:237], v180 offset:512
	ds_read_b64_tr_b16 v[238:239], v180 offset:2560
	ds_read_b64_tr_b16 v[240:241], v180 offset:1024
	ds_read_b64_tr_b16 v[242:243], v180 offset:3072
	ds_read_b64_tr_b16 v[248:249], v180 offset:1536
	ds_read_b64_tr_b16 v[250:251], v180 offset:3584
	s_nop 3
	v_max3_f32 v194, v80, v81, v82
	v_max3_f32 v195, v64, v65, v66
	v_max3_f32 v194, v194, v83, v84
	v_max3_f32 v195, v195, v67, v68
	s_waitcnt lgkmcnt(4)
	v_mfma_f32_32x32x16_bf16 v[32:47], v[148:151], v[232:235], v[32:47]
	ds_read_b64_tr_b16 v[232:233], v180 offset:4096
	ds_read_b64_tr_b16 v[234:235], v180 offset:6144
	v_max3_f32 v194, v194, v85, v86
	v_max3_f32 v195, v195, v69, v70
	v_max3_f32 v194, v194, v87, v88
	v_max3_f32 v195, v195, v71, v72
	v_mfma_f32_32x32x16_bf16 v[48:63], v[148:151], v[236:239], v[48:63]
	ds_read_b64_tr_b16 v[236:237], v180 offset:4608
	ds_read_b64_tr_b16 v[238:239], v180 offset:6656
	v_max3_f32 v194, v194, v89, v90
	v_max3_f32 v195, v195, v73, v74
	v_max3_f32 v194, v194, v91, v92
	v_max3_f32 v195, v195, v75, v76
	s_waitcnt lgkmcnt(4)
	v_mfma_f32_32x32x16_bf16 v[16:31], v[148:151], v[240:243], v[16:31]
	ds_read_b64_tr_b16 v[240:241], v180 offset:5120
	ds_read_b64_tr_b16 v[242:243], v180 offset:7168
	v_max3_f32 v194, v194, v93, v94
	v_max3_f32 v195, v195, v77, v78
	v_max3_f32 v194, v194, v95, v195
	v_max_f32_e32 v194, v194, v79
	v_mfma_f32_32x32x16_bf16 v[0:15], v[148:151], v[248:251], v[0:15]
	ds_read_b64_tr_b16 v[248:249], v180 offset:5632
	ds_read_b64_tr_b16 v[250:251], v180 offset:7680
	v_mov_b32_e32 v195, v194
	s_nop 1
	v_permlane32_swap_b32_e32 v194, v195
	v_max_f32_e32 v194, v194, v195
	s_waitcnt lgkmcnt(4)
	v_mfma_f32_32x32x16_bf16 v[32:47], v[152:155], v[232:235], v[32:47]
	ds_read_b64_tr_b16 v[232:233], v180 offset:8192
	ds_read_b64_tr_b16 v[234:235], v180 offset:10240
	v_sub_f32_e32 v195, v194, v210
	v_cmp_ge_f32_e32 vcc, s15, v195
	v_mfma_f32_32x32x16_bf16 v[48:63], v[152:155], v[236:239], v[48:63]
	ds_read_b64_tr_b16 v[236:237], v180 offset:8704
	ds_read_b64_tr_b16 v[238:239], v180 offset:10752
	s_cmp_eq_u64 vcc, exec
	s_cselect_b64 s[40:41], -1, 0
	s_cbranch_scc1 .Lattn_fast1p
	v_max_f32_e32 v194, v210, v194
	v_sub_f32_e32 v195, v210, v194
	v_mul_f32_e32 v195, 0x3dd53b94, v195
	v_exp_f32_e32 v214, v195
	v_mov_b32_e32 v210, v194
	s_branch .Lattn_join1p

; #define SBAR() __builtin_amdgcn_sched_barrier(0)
; #define LBAR() do { asm volatile("s_waitcnt lgkmcnt(0)" ::: "memory"); __builtin_amdgcn_s_barrier(); asm volatile("" ::: "memory"); } while (0)
; template <int D0> __device__ __forceinline__ void pv_one(f32x16& od, int vb, bf16x8 pa0, bf16x8 pa1, bf16x8 pa2, bf16x8 pa3) {
;   const s16x4 l0 = tr_read<v_rd_off(D0, 0, 0)>(vb), h0 = tr_read<v_rd_off(D0, 0, 1)>(vb), l1 = tr_read<v_rd_off(D0, 1, 0)>(vb), h1 = tr_read<v_rd_off(D0, 1, 1)>(vb);
;   const s16x4 l2 = tr_read<v_rd_off(D0, 2, 0)>(vb), h2 = tr_read<v_rd_off(D0, 2, 1)>(vb), l3 = tr_read<v_rd_off(D0, 3, 0)>(vb), h3 = tr_read<v_rd_off(D0, 3, 1)>(vb);
;   asm volatile("s_waitcnt lgkmcnt(0)" ::: "memory"); SBAR();
;     ...
;   od = __builtin_amdgcn_mfma_f32_32x32x16_bf16(pa0, PK(l0, h0), od, 0, 0, 0);
;   od = __builtin_amdgcn_mfma_f32_32x32x16_bf16(pa1, PK(l1, h1), od, 0, 0, 0);
;   od = __builtin_amdgcn_mfma_f32_32x32x16_bf16(pa2, PK(l2, h2), od, 0, 0, 0);
;   od = __builtin_amdgcn_mfma_f32_32x32x16_bf16(pa3, PK(l3, h3), od, 0, 0, 0);
;     ...
; }
; __device__ __forceinline__ void pv_d0(f32x16* o, int vb, bf16x8 pa0, bf16x8 pa1, bf16x8 pa2, bf16x8 pa3) {
;   pv_one<0>(o[0], vb, pa0, pa1, pa2, pa3); pv_one<1>(o[1], vb, pa0, pa1, pa2, pa3); pv_one<2>(o[2], vb, pa0, pa1, pa2, pa3); pv_one<3>(o[3], vb, pa0, pa1, pa2, pa3);
; __device__ __forceinline__ void attn_unit(const bf16_t* __restrict__ Qb, const bf16_t* __restrict__ Kn, const bf16_t* __restrict__ Vh, const bf16_t* __restrict__ Kr,
;                                           bf16_t* GO, int seq, char* lds, const int tid) {
;     ...
;   f32x16 pA0, pA1, pB0, pB1; float mnA, mnB, alA, alB; bf16x8 pa0, pa1, pa2, pa3; const int NT = seq / KVBLK;
;     ...
;   SLOAD(0, 0); SWRITE(0, 0); SLOAD(0, KVBLK); LBAR();
;   qkt(pA0, pA1, K_lds, qr, qrl, r32, hi); partialSM(pA0, pA1, m_reg, mnA, alA);
;   SWRITE(1, 0); if (2 < NT) SLOAD(0, 2 * KVBLK); LBAR();
;   int bc = 1;
;   for (int j = 1; j + 1 < NT; j += 2) {
;     const int bp = bc == 0 ? 2 : bc - 1, bn = bc == 2 ? 0 : bc + 1;
;     SBAR(); qkt(pB0, pB1, K_lds + bc * SHM_K, qr, qrl, r32, hi);
;     finishSM(pA0, pA1, alA, l_reg, pa0, pa1, pa2, pa3); SBAR();
;     SWRITE(bn, 0); SLOAD(0, (j + 2) * KVBLK); SBAR();
;     pv_d0(o, vb0 + bp * SHM_V, pa0, pa1, pa2, pa3); partialSM(pB0, pB1, m_reg, mnB, alB);
;     RESC(alB); LBAR();
.Lattn_join1p:
	v_mul_f32_e32 v194, 0xbdd53b94, v210
	s_waitcnt lgkmcnt(4)
	v_mfma_f32_32x32x16_bf16 v[16:31], v[152:155], v[240:243], v[16:31]
	ds_read_b64_tr_b16 v[240:241], v180 offset:9216
	ds_read_b64_tr_b16 v[242:243], v180 offset:11264
	v_fmamk_f32 v225, v80, 0x3dd53b94, v194
	v_fmamk_f32 v228, v81, 0x3dd53b94, v194
	v_fmamk_f32 v226, v82, 0x3dd53b94, v194
	v_fmamk_f32 v229, v83, 0x3dd53b94, v194
	v_mfma_f32_32x32x16_bf16 v[0:15], v[152:155], v[248:251], v[0:15]
	ds_read_b64_tr_b16 v[248:249], v180 offset:9728
	ds_read_b64_tr_b16 v[250:251], v180 offset:11776
	v_fmamk_f32 v150, v76, 0x3dd53b94, v194
	v_fmamk_f32 v151, v77, 0x3dd53b94, v194
	v_fmamk_f32 v148, v78, 0x3dd53b94, v194
	v_fmamk_f32 v149, v79, 0x3dd53b94, v194
	s_waitcnt lgkmcnt(4)
	v_mfma_f32_32x32x16_bf16 v[32:47], v[156:159], v[232:235], v[32:47]
	ds_read_b64_tr_b16 v[232:233], v180 offset:12288
	ds_read_b64_tr_b16 v[234:235], v180 offset:14336
	v_fmamk_f32 v227, v84, 0x3dd53b94, v194
	v_fmamk_f32 v230, v85, 0x3dd53b94, v194
	v_fmamk_f32 v223, v86, 0x3dd53b94, v194
	v_fmamk_f32 v224, v87, 0x3dd53b94, v194
	v_mfma_f32_32x32x16_bf16 v[48:63], v[156:159], v[236:239], v[48:63]
	ds_read_b64_tr_b16 v[236:237], v180 offset:12800
	ds_read_b64_tr_b16 v[238:239], v180 offset:14848
	v_fmamk_f32 v154, v72, 0x3dd53b94, v194
	v_fmamk_f32 v155, v73, 0x3dd53b94, v194
	v_fmamk_f32 v152, v74, 0x3dd53b94, v194
	v_fmamk_f32 v153, v75, 0x3dd53b94, v194
	s_waitcnt lgkmcnt(4)
	v_mfma_f32_32x32x16_bf16 v[16:31], v[156:159], v[240:243], v[16:31]
	ds_read_b64_tr_b16 v[240:241], v180 offset:13312
	ds_read_b64_tr_b16 v[242:243], v180 offset:15360
	v_fmamk_f32 v219, v88, 0x3dd53b94, v194
	v_fmamk_f32 v221, v89, 0x3dd53b94, v194
	v_fmamk_f32 v220, v90, 0x3dd53b94, v194
	v_fmamk_f32 v222, v91, 0x3dd53b94, v194
	v_mfma_f32_32x32x16_bf16 v[0:15], v[156:159], v[248:251], v[0:15]
	ds_read_b64_tr_b16 v[248:249], v180 offset:13824
	ds_read_b64_tr_b16 v[250:251], v180 offset:15872
	v_fmamk_f32 v158, v68, 0x3dd53b94, v194
	v_fmamk_f32 v159, v69, 0x3dd53b94, v194
	v_fmamk_f32 v156, v70, 0x3dd53b94, v194
	v_fmamk_f32 v157, v71, 0x3dd53b94, v194
	s_waitcnt lgkmcnt(0)
	s_barrier
	v_mfma_f32_32x32x16_bf16 v[32:47], v[160:163], v[232:235], v[32:47]
	ds_read_b128 v[232:235], v199 offset:12288
	v_fmamk_f32 v215, v92, 0x3dd53b94, v194
	v_fmamk_f32 v217, v93, 0x3dd53b94, v194
	v_fmamk_f32 v216, v94, 0x3dd53b94, v194
	v_fmamk_f32 v218, v95, 0x3dd53b94, v194
	v_mfma_f32_32x32x16_bf16 v[48:63], v[160:163], v[236:239], v[48:63]
	ds_read_b128 v[236:239], v199 offset:24576
	v_mfma_f32_32x32x16_bf16 v[16:31], v[160:163], v[240:243], v[16:31]
	ds_read_b128 v[240:243], v205 offset:12288
	v_mfma_f32_32x32x16_bf16 v[0:15], v[160:163], v[248:251], v[0:15]
	ds_read_b128 v[248:251], v205 offset:24576
	v_fmamk_f32 v162, v64, 0x3dd53b94, v194
	v_fmamk_f32 v163, v65, 0x3dd53b94, v194
	v_fmamk_f32 v160, v66, 0x3dd53b94, v194
	v_fmamk_f32 v161, v67, 0x3dd53b94, v194
	s_and_b64 vcc, exec, s[40:41]
	s_cbranch_vccnz .Lattn_skip_rs1p
	s_and_saveexec_b64 s[18:19], s[38:39]
	ds_write_b32 v175, v214 offset:128
	s_or_b64 exec, exec, s[18:19]
	s_waitcnt lgkmcnt(0)
	v_add_u32_e32 v194, v173, v164
	ds_read_b128 v[64:67], v194 offset:224
	ds_read_b128 v[68:71], v194 offset:192
	ds_read_b128 v[72:75], v194 offset:160
	ds_read_b128 v[76:79], v194 offset:128
	s_waitcnt lgkmcnt(0)
	v_pk_mul_f32 v[44:45], v[44:45], v[64:65]
	v_pk_mul_f32 v[46:47], v[46:47], v[66:67]
	v_pk_mul_f32 v[40:41], v[40:41], v[68:69]
	v_pk_mul_f32 v[42:43], v[42:43], v[70:71]
	v_pk_mul_f32 v[36:37], v[36:37], v[72:73]
	v_pk_mul_f32 v[38:39], v[38:39], v[74:75]
	v_pk_mul_f32 v[32:33], v[32:33], v[76:77]
	v_pk_mul_f32 v[34:35], v[34:35], v[78:79]
	v_pk_mul_f32 v[60:61], v[60:61], v[64:65]
	v_pk_mul_f32 v[62:63], v[62:63], v[66:67]
	v_pk_mul_f32 v[56:57], v[56:57], v[68:69]
	v_pk_mul_f32 v[58:59], v[58:59], v[70:71]
	v_pk_mul_f32 v[52:53], v[52:53], v[72:73]
	v_pk_mul_f32 v[54:55], v[54:55], v[74:75]
	v_pk_mul_f32 v[48:49], v[48:49], v[76:77]
	v_pk_mul_f32 v[50:51], v[50:51], v[78:79]
	v_pk_mul_f32 v[28:29], v[28:29], v[64:65]
	v_pk_mul_f32 v[30:31], v[30:31], v[66:67]
	v_pk_mul_f32 v[24:25], v[24:25], v[68:69]
	v_pk_mul_f32 v[26:27], v[26:27], v[70:71]
	v_pk_mul_f32 v[20:21], v[20:21], v[72:73]
	v_pk_mul_f32 v[22:23], v[22:23], v[74:75]
	v_pk_mul_f32 v[16:17], v[16:17], v[76:77]
	v_pk_mul_f32 v[18:19], v[18:19], v[78:79]
	v_pk_mul_f32 v[12:13], v[12:13], v[64:65]
	v_pk_mul_f32 v[14:15], v[14:15], v[66:67]
	v_pk_mul_f32 v[8:9], v[8:9], v[68:69]
	v_pk_mul_f32 v[10:11], v[10:11], v[70:71]
	v_pk_mul_f32 v[4:5], v[4:5], v[72:73]
	v_pk_mul_f32 v[6:7], v[6:7], v[74:75]
	v_pk_mul_f32 v[0:1], v[0:1], v[76:77]
	v_pk_mul_f32 v[2:3], v[2:3], v[78:79]
; #define SBAR() __builtin_amdgcn_sched_barrier(0)
; __device__ __forceinline__ void finishSM(f32x16& p0, f32x16& p1, float alpha, float& l_reg, bf16x8& pa0, bf16x8& pa1, bf16x8& pa2, bf16x8& pa3) {
; #pragma unroll
;   for (int r = 0; r < 16; ++r) p1[r] = __builtin_amdgcn_exp2f(p1[r]);
;   float ps = 0;
; #pragma unroll
;   for (int r = 0; r < 16; ++r) ps += p0[r];
; #pragma unroll
;   for (int r = 0; r < 16; ++r) ps += p1[r];
;   { auto rr = __builtin_amdgcn_permlane32_swap(__float_as_uint(ps), __float_as_uint(ps), false, false);
;     ps = __uint_as_float(rr[0]) + __uint_as_float(rr[1]); }
;   l_reg = l_reg * alpha + ps;
;     ...
;   PK4(p0, 0, pa0); PK4(p0, 8, pa1); PK4(p1, 0, pa2); PK4(p1, 8, pa3);
;     ...
; }
; __device__ __forceinline__ void qkt(f32x16& p0, f32x16& p1, const char* Ks, const bf16x8* qr, const char* qrl, int r32, int hi) {
;   p0 = f32x16{}; p1 = f32x16{};
; #pragma unroll
;   for (int d0 = 0; d0 < 8; ++d0) { int cb = (d0 * 16 + hi * 8) * 2;
;     bf16x8 b0 = *reinterpret_cast<const bf16x8*>(Ks + KSWZ(r32, cb));
;     bf16x8 b1 = *reinterpret_cast<const bf16x8*>(Ks + KSWZ(32 + r32, cb));
;     p0 = __builtin_amdgcn_mfma_f32_32x32x16_bf16(b0, qr[d0], p0, 0, 0, 0);
;     p1 = __builtin_amdgcn_mfma_f32_32x32x16_bf16(b1, qr[d0], p1, 0, 0, 0); }
; #pragma unroll
;   for (int d0 = 8; d0 < 12; ++d0) { int cb = (d0 * 16 + hi * 8) * 2;
;     bf16x8 b0 = *reinterpret_cast<const bf16x8*>(Ks + KSWZ(r32, cb));
;     bf16x8 b1 = *reinterpret_cast<const bf16x8*>(Ks + KSWZ(32 + r32, cb));
;     bf16x8 qf = *reinterpret_cast<const bf16x8*>(qrl + (((2 * (d0 - 8) + hi) ^ ((r32 >> 1) & 7)) << 4));
;     p0 = __builtin_amdgcn_mfma_f32_32x32x16_bf16(b0, qf, p0, 0, 0, 0);
;     p1 = __builtin_amdgcn_mfma_f32_32x32x16_bf16(b1, qf, p1, 0, 0, 0); }
; }
; __device__ __forceinline__ void attn_unit(const bf16_t* __restrict__ Qb, const bf16_t* __restrict__ Kn, const bf16_t* __restrict__ Vh, const bf16_t* __restrict__ Kr,
;                                           bf16_t* GO, int seq, char* lds, const int tid) {
;     ...
;     SBAR(); qkt(pA0, pA1, K_lds + bn * SHM_K, qr, qrl, r32, hi);
;     finishSM(pB0, pB1, alB, l_reg, pa0, pa1, pa2, pa3); SBAR();
;     SWRITE(bp, 0); if (j + 3 < NT) SLOAD(0, (j + 3) * KVBLK); SBAR();
.Lattn_skip_rs1p:
	v_exp_f32_e32 v225, v225
	v_exp_f32_e32 v228, v228
	v_exp_f32_e32 v226, v226
	v_add_f32_e32 v211, v225, v228
	s_waitcnt lgkmcnt(2)
	v_mfma_f32_32x32x16_bf16 v[80:95], v[232:235], v[124:127], 0
	ds_read_b128 v[232:235], v206 offset:12288
	v_exp_f32_e32 v229, v229
	v_add_f32_e32 v211, v226, v211
	v_exp_f32_e32 v227, v227
	v_add_f32_e32 v211, v229, v211
	v_mfma_f32_32x32x16_bf16 v[64:79], v[236:239], v[124:127], 0
	ds_read_b128 v[236:239], v206 offset:24576
	v_exp_f32_e32 v230, v230
	v_add_f32_e32 v211, v227, v211
	v_exp_f32_e32 v223, v223
	v_add_f32_e32 v211, v230, v211
	s_waitcnt lgkmcnt(2)
	v_mfma_f32_32x32x16_bf16 v[80:95], v[240:243], v[120:123], v[80:95]
	ds_read_b128 v[240:243], v208 offset:12288
	v_exp_f32_e32 v224, v224
	v_add_f32_e32 v211, v223, v211
	v_exp_f32_e32 v219, v219
	v_add_f32_e32 v211, v224, v211
	v_mfma_f32_32x32x16_bf16 v[64:79], v[248:251], v[120:123], v[64:79]
	ds_read_b128 v[248:251], v208 offset:24576
	v_exp_f32_e32 v221, v221
	v_add_f32_e32 v211, v219, v211
	v_exp_f32_e32 v220, v220
	v_add_f32_e32 v211, v221, v211
	s_waitcnt lgkmcnt(2)
	v_mfma_f32_32x32x16_bf16 v[80:95], v[232:235], v[116:119], v[80:95]
	ds_read_b128 v[232:235], v207 offset:12288
	v_exp_f32_e32 v222, v222
	v_add_f32_e32 v211, v220, v211
	v_exp_f32_e32 v215, v215
	v_add_f32_e32 v211, v222, v211
	v_mfma_f32_32x32x16_bf16 v[64:79], v[236:239], v[116:119], v[64:79]
	ds_read_b128 v[236:239], v207 offset:24576
	v_exp_f32_e32 v217, v217
	v_add_f32_e32 v211, v215, v211
	v_exp_f32_e32 v216, v216
	v_add_f32_e32 v211, v217, v211
	s_waitcnt lgkmcnt(2)
	v_mfma_f32_32x32x16_bf16 v[80:95], v[240:243], v[112:115], v[80:95]
	ds_read_b128 v[240:243], v204 offset:12288
	v_exp_f32_e32 v218, v218
	v_add_f32_e32 v211, v216, v211
	v_exp_f32_e32 v162, v162
	v_add_f32_e32 v211, v218, v211
	v_mfma_f32_32x32x16_bf16 v[64:79], v[248:251], v[112:115], v[64:79]
	ds_read_b128 v[248:251], v204 offset:24576
	v_exp_f32_e32 v163, v163
	v_exp_f32_e32 v160, v160
	v_exp_f32_e32 v161, v161
	s_waitcnt lgkmcnt(2)
	v_mfma_f32_32x32x16_bf16 v[80:95], v[232:235], v[108:111], v[80:95]
	ds_read_b128 v[232:235], v203 offset:12288
	v_exp_f32_e32 v158, v158
	v_exp_f32_e32 v159, v159
	v_exp_f32_e32 v156, v156
	v_mfma_f32_32x32x16_bf16 v[64:79], v[236:239], v[108:111], v[64:79]
	ds_read_b128 v[236:239], v203 offset:24576
	v_exp_f32_e32 v157, v157
	v_exp_f32_e32 v154, v154
	v_exp_f32_e32 v155, v155
	s_waitcnt lgkmcnt(2)
	v_mfma_f32_32x32x16_bf16 v[80:95], v[240:243], v[104:107], v[80:95]
	ds_read_b128 v[240:243], v200 offset:12288
	v_exp_f32_e32 v152, v152
	v_exp_f32_e32 v153, v153
	v_exp_f32_e32 v150, v150
	v_mfma_f32_32x32x16_bf16 v[64:79], v[248:251], v[104:107], v[64:79]
	ds_read_b128 v[248:251], v200 offset:24576
	v_exp_f32_e32 v151, v151
	v_exp_f32_e32 v148, v148
	v_exp_f32_e32 v149, v149
	s_waitcnt lgkmcnt(2)
	v_mfma_f32_32x32x16_bf16 v[80:95], v[232:235], v[100:103], v[80:95]
	ds_read_b128 v[232:235], v191 offset:12288
	v_add_f32_e32 v212, v162, v163
	v_add_f32_e32 v212, v160, v212
	v_add_f32_e32 v212, v161, v212
	v_add_f32_e32 v212, v158, v212
	v_add_f32_e32 v212, v159, v212
	v_add_f32_e32 v212, v156, v212
	v_mfma_f32_32x32x16_bf16 v[64:79], v[236:239], v[100:103], v[64:79]
	ds_read_b128 v[236:239], v202 offset:24576
	v_add_f32_e32 v212, v157, v212
	v_add_f32_e32 v212, v154, v212
	v_add_f32_e32 v212, v155, v212
	v_add_f32_e32 v212, v152, v212
	v_add_f32_e32 v212, v153, v212
	v_add_f32_e32 v212, v150, v212
	s_waitcnt lgkmcnt(2)
	v_mfma_f32_32x32x16_bf16 v[80:95], v[240:243], v[96:99], v[80:95]
	ds_read_b128 v[240:243], v182
	v_add_f32_e32 v212, v151, v212
	v_add_f32_e32 v212, v148, v212
	v_add_f32_e32 v212, v149, v212
	v_add_f32_e32 v211, v211, v212
	v_mov_b32_e32 v212, v211
	v_add_u32_e32 v194, s31, v183
	s_waitcnt vmcnt(4)
	v_mfma_f32_32x32x16_bf16 v[64:79], v[248:251], v[96:99], v[64:79]
	ds_read_b128 v[248:251], v198 offset:12288
	ds_write_b128 v194, v[140:143]
	v_add_u32_e32 v194, s31, v184
	s_add_i32 s73, s73, 2
	s_cmp_ge_u32 s73, s45
	s_waitcnt vmcnt(2)
	ds_write_b128 v194, v[144:147]
	s_cselect_b64 s[28:29], -1, 0
	ds_write_b128 v185, v[136:139] offset:36864
	s_waitcnt vmcnt(1)
	ds_write_b128 v185, v[132:135] offset:49152
	s_and_b64 vcc, exec, s[28:29]
	s_waitcnt lgkmcnt(5)
	v_mfma_f32_32x32x16_bf16 v[80:95], v[232:235], v[240:243], v[80:95]
	ds_read_b128 v[232:235], v201 offset:24576
	s_waitcnt vmcnt(0)
	ds_write_b128 v186, v[128:131] offset:36864
	v_mfma_f32_32x32x16_bf16 v[64:79], v[236:239], v[240:243], v[64:79]
	ds_read_b128 v[236:239], v181
	ds_read_b128 v[240:243], v187 offset:12288
	s_cbranch_vccnz .Lattn_noloadp
	v_add_co_u32_e32 v128, vcc, 0xfffe0000, v168
	s_nop 1
	v_addc_co_u32_e32 v129, vcc, -1, v169, vcc
	global_load_dwordx4 v[140:143], v[128:129], off
	global_load_dwordx4 v[136:139], v[128:129], off offset:-256
	global_load_dwordx4 v[144:147], v[168:169], off
	global_load_dwordx4 v[132:135], v[168:169], off offset:-256
	s_nop 0
	global_load_dwordx4 v[128:131], v[166:167], off
; __device__ __forceinline__ void finishSM(f32x16& p0, f32x16& p1, float alpha, float& l_reg, bf16x8& pa0, bf16x8& pa1, bf16x8& pa2, bf16x8& pa3) {
;     ...
;   PK4(p0, 0, pa0); PK4(p0, 8, pa1); PK4(p1, 0, pa2); PK4(p1, 8, pa3);
;     ...
; }
; __device__ __forceinline__ void qkt(f32x16& p0, f32x16& p1, const char* Ks, const bf16x8* qr, const char* qrl, int r32, int hi) {
;   p0 = f32x16{}; p1 = f32x16{};
; #pragma unroll
;   for (int d0 = 0; d0 < 8; ++d0) { int cb = (d0 * 16 + hi * 8) * 2;
;     bf16x8 b0 = *reinterpret_cast<const bf16x8*>(Ks + KSWZ(r32, cb));
;     bf16x8 b1 = *reinterpret_cast<const bf16x8*>(Ks + KSWZ(32 + r32, cb));
;     p0 = __builtin_amdgcn_mfma_f32_32x32x16_bf16(b0, qr[d0], p0, 0, 0, 0);
;     p1 = __builtin_amdgcn_mfma_f32_32x32x16_bf16(b1, qr[d0], p1, 0, 0, 0); }
; #pragma unroll
;   for (int d0 = 8; d0 < 12; ++d0) { int cb = (d0 * 16 + hi * 8) * 2;
;     bf16x8 b0 = *reinterpret_cast<const bf16x8*>(Ks + KSWZ(r32, cb));
;     bf16x8 b1 = *reinterpret_cast<const bf16x8*>(Ks + KSWZ(32 + r32, cb));
;     bf16x8 qf = *reinterpret_cast<const bf16x8*>(qrl + (((2 * (d0 - 8) + hi) ^ ((r32 >> 1) & 7)) << 4));
;     p0 = __builtin_amdgcn_mfma_f32_32x32x16_bf16(b0, qf, p0, 0, 0, 0);
;     p1 = __builtin_amdgcn_mfma_f32_32x32x16_bf16(b1, qf, p1, 0, 0, 0); }
; }
; __device__ __forceinline__ int v_st(int k, int c) { const int kk = (k & ~0xC) | ((k & 4) << 1) | ((k & 8) >> 1); return ((kk >> 3) * 4 + (c >> 5)) * 512 + ((kk & 7) * 32 + (c & 31)) * 2; }
; __device__ __forceinline__ int v_rd_base(int lane) { return ((lane & 3) << 3) | (((lane >> 2) & 3) << 6) | (((lane >> 4) & 1) << 5) | (((lane >> 5) & 1) << 8); }
; template <int OFF> __device__ __forceinline__ s16x4 tr_read(int vb) {
;   s16x4 r; asm volatile("ds_read_b64_tr_b16 %0, %1 offset:%2" : "=&v"(r) : "v"(vb), "i"(OFF) : "memory"); return r;
; }
; template <int D0> __device__ __forceinline__ void pv_one(f32x16& od, int vb, bf16x8 pa0, bf16x8 pa1, bf16x8 pa2, bf16x8 pa3) {
;   const s16x4 l0 = tr_read<v_rd_off(D0, 0, 0)>(vb), h0 = tr_read<v_rd_off(D0, 0, 1)>(vb), l1 = tr_read<v_rd_off(D0, 1, 0)>(vb), h1 = tr_read<v_rd_off(D0, 1, 1)>(vb);
;   const s16x4 l2 = tr_read<v_rd_off(D0, 2, 0)>(vb), h2 = tr_read<v_rd_off(D0, 2, 1)>(vb), l3 = tr_read<v_rd_off(D0, 3, 0)>(vb), h3 = tr_read<v_rd_off(D0, 3, 1)>(vb);
;   asm volatile("s_waitcnt lgkmcnt(0)" ::: "memory"); SBAR();
.Lattn_noloadp:
	s_waitcnt lgkmcnt(1)
	v_mfma_f32_32x32x16_bf16 v[80:95], v[248:251], v[236:239], v[80:95]
	ds_read_b128 v[248:251], v189 offset:24576
	v_cvt_pk_bf16_f32 v158, v158, v159
	v_cvt_pk_bf16_f32 v159, v156, v157
	v_permlane32_swap_b32_e32 v211, v212
	v_cvt_pk_bf16_f32 v156, v162, v163
	v_cvt_pk_bf16_f32 v157, v160, v161
	v_cvt_pk_bf16_f32 v160, v154, v155
	v_mfma_f32_32x32x16_bf16 v[64:79], v[232:235], v[236:239], v[64:79]
	ds_read_b128 v[232:235], v179
	ds_read_b128 v[236:239], v188 offset:12288
	v_cvt_pk_bf16_f32 v161, v152, v153
	v_cvt_pk_bf16_f32 v162, v150, v151
	v_cvt_pk_bf16_f32 v163, v148, v149
	v_add_f32_e32 v211, v211, v212
	v_cvt_pk_bf16_f32 v148, v225, v228
	v_cvt_pk_bf16_f32 v149, v226, v229
	s_waitcnt lgkmcnt(1)
	v_mfma_f32_32x32x16_bf16 v[80:95], v[240:243], v[232:235], v[80:95]
	ds_read_b128 v[240:243], v190 offset:24576
	v_cvt_pk_bf16_f32 v150, v227, v230
	v_cvt_pk_bf16_f32 v151, v223, v224
	v_cvt_pk_bf16_f32 v152, v219, v221
	v_cvt_pk_bf16_f32 v153, v220, v222
	v_cvt_pk_bf16_f32 v154, v215, v217
	v_cvt_pk_bf16_f32 v155, v216, v218
	v_mfma_f32_32x32x16_bf16 v[64:79], v[248:251], v[232:235], v[64:79]
	ds_read_b128 v[248:251], v177
	v_fma_f32 v176, v214, v176, v211
	s_waitcnt lgkmcnt(0)
	v_mfma_f32_32x32x16_bf16 v[80:95], v[236:239], v[248:251], v[80:95]
	v_mfma_f32_32x32x16_bf16 v[64:79], v[240:243], v[248:251], v[64:79]
	v_lshl_add_u32 v231, s76, 14, v178
	ds_read_b64_tr_b16 v[232:233], v231 offset:0
	ds_read_b64_tr_b16 v[234:235], v231 offset:2048
	ds_read_b64_tr_b16 v[236:237], v231 offset:512
	ds_read_b64_tr_b16 v[238:239], v231 offset:2560
	ds_read_b64_tr_b16 v[240:241], v231 offset:1024
	ds_read_b64_tr_b16 v[242:243], v231 offset:3072
	ds_read_b64_tr_b16 v[248:249], v231 offset:1536
	ds_read_b64_tr_b16 v[250:251], v231 offset:3584
	s_nop 3
	v_max3_f32 v194, v80, v81, v82
	v_max3_f32 v195, v64, v65, v66
	v_max3_f32 v194, v194, v83, v84
	v_max3_f32 v195, v195, v67, v68
	s_waitcnt lgkmcnt(4)
	v_mfma_f32_32x32x16_bf16 v[32:47], v[148:151], v[232:235], v[32:47]
	ds_read_b64_tr_b16 v[232:233], v231 offset:4096
	ds_read_b64_tr_b16 v[234:235], v231 offset:6144
	v_max3_f32 v194, v194, v85, v86
	v_max3_f32 v195, v195, v69, v70
	v_max3_f32 v194, v194, v87, v88
	v_max3_f32 v195, v195, v71, v72
	v_mfma_f32_32x32x16_bf16 v[48:63], v[148:151], v[236:239], v[48:63]
	ds_read_b64_tr_b16 v[236:237], v231 offset:4608
	ds_read_b64_tr_b16 v[238:239], v231 offset:6656
	v_max3_f32 v194, v194, v89, v90
	v_max3_f32 v195, v195, v73, v74
	v_max3_f32 v194, v194, v91, v92
	v_max3_f32 v195, v195, v75, v76
	s_waitcnt lgkmcnt(4)
	v_mfma_f32_32x32x16_bf16 v[16:31], v[148:151], v[240:243], v[16:31]
	ds_read_b64_tr_b16 v[240:241], v231 offset:5120
	ds_read_b64_tr_b16 v[242:243], v231 offset:7168
	v_max3_f32 v194, v194, v93, v94
	v_max3_f32 v195, v195, v77, v78
	v_max3_f32 v194, v194, v95, v195
	v_max_f32_e32 v194, v194, v79
	v_mfma_f32_32x32x16_bf16 v[0:15], v[148:151], v[248:251], v[0:15]
	ds_read_b64_tr_b16 v[248:249], v231 offset:5632
	ds_read_b64_tr_b16 v[250:251], v231 offset:7680
	v_mov_b32_e32 v195, v194
	s_nop 1
	v_permlane32_swap_b32_e32 v194, v195
	v_max_f32_e32 v194, v194, v195
	s_waitcnt lgkmcnt(4)
	v_mfma_f32_32x32x16_bf16 v[32:47], v[152:155], v[232:235], v[32:47]
	ds_read_b64_tr_b16 v[232:233], v231 offset:8192
	ds_read_b64_tr_b16 v[234:235], v231 offset:10240
	v_sub_f32_e32 v195, v194, v210
	v_cmp_ge_f32_e32 vcc, s15, v195
	v_mfma_f32_32x32x16_bf16 v[48:63], v[152:155], v[236:239], v[48:63]
	ds_read_b64_tr_b16 v[236:237], v231 offset:8704
	ds_read_b64_tr_b16 v[238:239], v231 offset:10752
	s_cmp_eq_u64 vcc, exec
	s_cselect_b64 s[40:41], -1, 0
	s_cbranch_scc1 .Lattn_fast2p
	v_max_f32_e32 v194, v210, v194
	v_sub_f32_e32 v195, v210, v194
	v_mul_f32_e32 v195, 0x3dd53b94, v195
	v_exp_f32_e32 v213, v195
	v_mov_b32_e32 v210, v194
	s_branch .Lattn_join2p

; #define SBAR() __builtin_amdgcn_sched_barrier(0)
; template <int D0> __device__ __forceinline__ void pv_one(f32x16& od, int vb, bf16x8 pa0, bf16x8 pa1, bf16x8 pa2, bf16x8 pa3) {
;   const s16x4 l0 = tr_read<v_rd_off(D0, 0, 0)>(vb), h0 = tr_read<v_rd_off(D0, 0, 1)>(vb), l1 = tr_read<v_rd_off(D0, 1, 0)>(vb), h1 = tr_read<v_rd_off(D0, 1, 1)>(vb);
;   const s16x4 l2 = tr_read<v_rd_off(D0, 2, 0)>(vb), h2 = tr_read<v_rd_off(D0, 2, 1)>(vb), l3 = tr_read<v_rd_off(D0, 3, 0)>(vb), h3 = tr_read<v_rd_off(D0, 3, 1)>(vb);
;   asm volatile("s_waitcnt lgkmcnt(0)" ::: "memory"); SBAR();
;     ...
;   od = __builtin_amdgcn_mfma_f32_32x32x16_bf16(pa0, PK(l0, h0), od, 0, 0, 0);
;   od = __builtin_amdgcn_mfma_f32_32x32x16_bf16(pa1, PK(l1, h1), od, 0, 0, 0);
;   od = __builtin_amdgcn_mfma_f32_32x32x16_bf16(pa2, PK(l2, h2), od, 0, 0, 0);
;   od = __builtin_amdgcn_mfma_f32_32x32x16_bf16(pa3, PK(l3, h3), od, 0, 0, 0);
;     ...
; }
; __device__ __forceinline__ void pv_d0(f32x16* o, int vb, bf16x8 pa0, bf16x8 pa1, bf16x8 pa2, bf16x8 pa3) {
;   pv_one<0>(o[0], vb, pa0, pa1, pa2, pa3); pv_one<1>(o[1], vb, pa0, pa1, pa2, pa3); pv_one<2>(o[2], vb, pa0, pa1, pa2, pa3); pv_one<3>(o[3], vb, pa0, pa1, pa2, pa3);
; __device__ __forceinline__ void attn_unit(const bf16_t* __restrict__ Qb, const bf16_t* __restrict__ Kn, const bf16_t* __restrict__ Vh, const bf16_t* __restrict__ Kr,
;                                           bf16_t* GO, int seq, char* lds, const int tid) {
;     ...
;   f32x16 pA0, pA1, pB0, pB1; float mnA, mnB, alA, alB; bf16x8 pa0, pa1, pa2, pa3; const int NT = seq / KVBLK;
;     ...
;   SLOAD(0, 0); SWRITE(0, 0); SLOAD(0, KVBLK); LBAR();
;   qkt(pA0, pA1, K_lds, qr, qrl, r32, hi); partialSM(pA0, pA1, m_reg, mnA, alA);
;   SWRITE(1, 0); if (2 < NT) SLOAD(0, 2 * KVBLK); LBAR();
;   int bc = 1;
;   for (int j = 1; j + 1 < NT; j += 2) {
;     const int bp = bc == 0 ? 2 : bc - 1, bn = bc == 2 ? 0 : bc + 1;
;     SBAR(); qkt(pB0, pB1, K_lds + bc * SHM_K, qr, qrl, r32, hi);
;     finishSM(pA0, pA1, alA, l_reg, pa0, pa1, pa2, pa3); SBAR();
;     SWRITE(bn, 0); SLOAD(0, (j + 2) * KVBLK); SBAR();
;     pv_d0(o, vb0 + bp * SHM_V, pa0, pa1, pa2, pa3); partialSM(pB0, pB1, m_reg, mnB, alB);
;     RESC(alB); LBAR();
;     SBAR(); qkt(pA0, pA1, K_lds + bn * SHM_K, qr, qrl, r32, hi);
;     finishSM(pB0, pB1, alB, l_reg, pa0, pa1, pa2, pa3); SBAR();
;     SWRITE(bp, 0); if (j + 3 < NT) SLOAD(0, (j + 3) * KVBLK); SBAR();
.Lattn_join2p:
	v_mul_f32_e32 v194, 0xbdd53b94, v210
	s_waitcnt lgkmcnt(4)
	v_mfma_f32_32x32x16_bf16 v[16:31], v[152:155], v[240:243], v[16:31]
	ds_read_b64_tr_b16 v[240:241], v231 offset:9216
	ds_read_b64_tr_b16 v[242:243], v231 offset:11264
	v_fmamk_f32 v225, v80, 0x3dd53b94, v194
	v_fmamk_f32 v228, v81, 0x3dd53b94, v194
	v_fmamk_f32 v226, v82, 0x3dd53b94, v194
	v_fmamk_f32 v229, v83, 0x3dd53b94, v194
	v_mfma_f32_32x32x16_bf16 v[0:15], v[152:155], v[248:251], v[0:15]
	ds_read_b64_tr_b16 v[248:249], v231 offset:9728
	ds_read_b64_tr_b16 v[250:251], v231 offset:11776
	v_fmamk_f32 v150, v76, 0x3dd53b94, v194
	v_fmamk_f32 v151, v77, 0x3dd53b94, v194
	v_fmamk_f32 v148, v78, 0x3dd53b94, v194
	v_fmamk_f32 v149, v79, 0x3dd53b94, v194
	s_waitcnt lgkmcnt(4)
	v_mfma_f32_32x32x16_bf16 v[32:47], v[156:159], v[232:235], v[32:47]
	ds_read_b64_tr_b16 v[232:233], v231 offset:12288
	ds_read_b64_tr_b16 v[234:235], v231 offset:14336
	v_fmamk_f32 v227, v84, 0x3dd53b94, v194
	v_fmamk_f32 v230, v85, 0x3dd53b94, v194
	v_fmamk_f32 v223, v86, 0x3dd53b94, v194
	v_fmamk_f32 v224, v87, 0x3dd53b94, v194
	v_mfma_f32_32x32x16_bf16 v[48:63], v[156:159], v[236:239], v[48:63]
	ds_read_b64_tr_b16 v[236:237], v231 offset:12800
	ds_read_b64_tr_b16 v[238:239], v231 offset:14848
	v_fmamk_f32 v154, v72, 0x3dd53b94, v194
	v_fmamk_f32 v155, v73, 0x3dd53b94, v194
	v_fmamk_f32 v152, v74, 0x3dd53b94, v194
	v_fmamk_f32 v153, v75, 0x3dd53b94, v194
	s_waitcnt lgkmcnt(4)
	v_mfma_f32_32x32x16_bf16 v[16:31], v[156:159], v[240:243], v[16:31]
	ds_read_b64_tr_b16 v[240:241], v231 offset:13312
	ds_read_b64_tr_b16 v[242:243], v231 offset:15360
	v_fmamk_f32 v219, v88, 0x3dd53b94, v194
	v_fmamk_f32 v221, v89, 0x3dd53b94, v194
	v_fmamk_f32 v220, v90, 0x3dd53b94, v194
	v_fmamk_f32 v222, v91, 0x3dd53b94, v194
	v_mfma_f32_32x32x16_bf16 v[0:15], v[156:159], v[248:251], v[0:15]
	ds_read_b64_tr_b16 v[248:249], v231 offset:13824
	ds_read_b64_tr_b16 v[250:251], v231 offset:15872
	v_fmamk_f32 v158, v68, 0x3dd53b94, v194
	v_fmamk_f32 v159, v69, 0x3dd53b94, v194
	v_fmamk_f32 v156, v70, 0x3dd53b94, v194
	v_fmamk_f32 v157, v71, 0x3dd53b94, v194
	s_waitcnt lgkmcnt(0)
	s_barrier
	v_mfma_f32_32x32x16_bf16 v[32:47], v[160:163], v[232:235], v[32:47]
	ds_read_b128 v[232:235], v199 offset:36864
	v_fmamk_f32 v215, v92, 0x3dd53b94, v194
	v_fmamk_f32 v217, v93, 0x3dd53b94, v194
	v_fmamk_f32 v216, v94, 0x3dd53b94, v194
	v_fmamk_f32 v218, v95, 0x3dd53b94, v194
	v_mfma_f32_32x32x16_bf16 v[48:63], v[160:163], v[236:239], v[48:63]
	ds_read_b128 v[236:239], v199 offset:49152
	v_mfma_f32_32x32x16_bf16 v[16:31], v[160:163], v[240:243], v[16:31]
	ds_read_b128 v[240:243], v205 offset:36864
	v_mfma_f32_32x32x16_bf16 v[0:15], v[160:163], v[248:251], v[0:15]
	ds_read_b128 v[248:251], v205 offset:49152
	v_fmamk_f32 v162, v64, 0x3dd53b94, v194
	v_fmamk_f32 v163, v65, 0x3dd53b94, v194
	v_fmamk_f32 v160, v66, 0x3dd53b94, v194
	v_fmamk_f32 v161, v67, 0x3dd53b94, v194
	s_and_b64 vcc, exec, s[40:41]
	s_cbranch_vccnz .Lattn_skip_rs2p
	s_and_saveexec_b64 s[18:19], s[38:39]
	ds_write_b32 v175, v213 offset:128
	s_or_b64 exec, exec, s[18:19]
	s_waitcnt lgkmcnt(0)
	v_add_u32_e32 v194, v173, v164
	ds_read_b128 v[64:67], v194 offset:224
	ds_read_b128 v[68:71], v194 offset:192
	ds_read_b128 v[72:75], v194 offset:160
	ds_read_b128 v[76:79], v194 offset:128
	s_waitcnt lgkmcnt(0)
	v_pk_mul_f32 v[44:45], v[44:45], v[64:65]
	v_pk_mul_f32 v[46:47], v[46:47], v[66:67]
	v_pk_mul_f32 v[40:41], v[40:41], v[68:69]
	v_pk_mul_f32 v[42:43], v[42:43], v[70:71]
	v_pk_mul_f32 v[36:37], v[36:37], v[72:73]
	v_pk_mul_f32 v[38:39], v[38:39], v[74:75]
	v_pk_mul_f32 v[32:33], v[32:33], v[76:77]
	v_pk_mul_f32 v[34:35], v[34:35], v[78:79]
	v_pk_mul_f32 v[60:61], v[60:61], v[64:65]
	v_pk_mul_f32 v[62:63], v[62:63], v[66:67]
	v_pk_mul_f32 v[56:57], v[56:57], v[68:69]
	v_pk_mul_f32 v[58:59], v[58:59], v[70:71]
	v_pk_mul_f32 v[52:53], v[52:53], v[72:73]
	v_pk_mul_f32 v[54:55], v[54:55], v[74:75]
	v_pk_mul_f32 v[48:49], v[48:49], v[76:77]
	v_pk_mul_f32 v[50:51], v[50:51], v[78:79]
	v_pk_mul_f32 v[28:29], v[28:29], v[64:65]
	v_pk_mul_f32 v[30:31], v[30:31], v[66:67]
	v_pk_mul_f32 v[24:25], v[24:25], v[68:69]
	v_pk_mul_f32 v[26:27], v[26:27], v[70:71]
	v_pk_mul_f32 v[20:21], v[20:21], v[72:73]
	v_pk_mul_f32 v[22:23], v[22:23], v[74:75]
	v_pk_mul_f32 v[16:17], v[16:17], v[76:77]
	v_pk_mul_f32 v[18:19], v[18:19], v[78:79]
	v_pk_mul_f32 v[12:13], v[12:13], v[64:65]
	v_pk_mul_f32 v[14:15], v[14:15], v[66:67]
	v_pk_mul_f32 v[8:9], v[8:9], v[68:69]
	v_pk_mul_f32 v[10:11], v[10:11], v[70:71]
	v_pk_mul_f32 v[4:5], v[4:5], v[72:73]
	v_pk_mul_f32 v[6:7], v[6:7], v[74:75]
	v_pk_mul_f32 v[0:1], v[0:1], v[76:77]
	v_pk_mul_f32 v[2:3], v[2:3], v[78:79]
.Lattn_skip_rs2p:
	s_movk_i32 s34, 0x6000
	s_mov_b64 s[18:19], 0x4000
	v_lshl_add_u64 v[166:167], v[166:167], 0, s[18:19]
	v_lshl_add_u64 v[168:169], v[168:169], 0, s[10:11]
	s_and_b64 vcc, exec, s[28:29]
	s_cbranch_vccnz .LBB0_1163
	s_mov_b32 s76, s30
	v_mov_b32_e32 v209, v213
; #define SBAR() __builtin_amdgcn_sched_barrier(0)
; __device__ __forceinline__ void finishSM(f32x16& p0, f32x16& p1, float alpha, float& l_reg, bf16x8& pa0, bf16x8& pa1, bf16x8& pa2, bf16x8& pa3) {
; #pragma unroll
;   for (int r = 0; r < 16; ++r) p1[r] = __builtin_amdgcn_exp2f(p1[r]);
;   float ps = 0;
; #pragma unroll
;   for (int r = 0; r < 16; ++r) ps += p0[r];
; #pragma unroll
;   for (int r = 0; r < 16; ++r) ps += p1[r];
;   { auto rr = __builtin_amdgcn_permlane32_swap(__float_as_uint(ps), __float_as_uint(ps), false, false);
;     ps = __uint_as_float(rr[0]) + __uint_as_float(rr[1]); }
;   l_reg = l_reg * alpha + ps;
;     ...
;   PK4(p0, 0, pa0); PK4(p0, 8, pa1); PK4(p1, 0, pa2); PK4(p1, 8, pa3);
;     ...
; }
; __device__ __forceinline__ void qkt(f32x16& p0, f32x16& p1, const char* Ks, const bf16x8* qr, const char* qrl, int r32, int hi) {
;   p0 = f32x16{}; p1 = f32x16{};
; #pragma unroll
;   for (int d0 = 0; d0 < 8; ++d0) { int cb = (d0 * 16 + hi * 8) * 2;
;     bf16x8 b0 = *reinterpret_cast<const bf16x8*>(Ks + KSWZ(r32, cb));
;     bf16x8 b1 = *reinterpret_cast<const bf16x8*>(Ks + KSWZ(32 + r32, cb));
;     p0 = __builtin_amdgcn_mfma_f32_32x32x16_bf16(b0, qr[d0], p0, 0, 0, 0);
;     p1 = __builtin_amdgcn_mfma_f32_32x32x16_bf16(b1, qr[d0], p1, 0, 0, 0); }
; #pragma unroll
;   for (int d0 = 8; d0 < 12; ++d0) { int cb = (d0 * 16 + hi * 8) * 2;
;     bf16x8 b0 = *reinterpret_cast<const bf16x8*>(Ks + KSWZ(r32, cb));
;     bf16x8 b1 = *reinterpret_cast<const bf16x8*>(Ks + KSWZ(32 + r32, cb));
;     bf16x8 qf = *reinterpret_cast<const bf16x8*>(qrl + (((2 * (d0 - 8) + hi) ^ ((r32 >> 1) & 7)) << 4));
;     p0 = __builtin_amdgcn_mfma_f32_32x32x16_bf16(b0, qf, p0, 0, 0, 0);
;     p1 = __builtin_amdgcn_mfma_f32_32x32x16_bf16(b1, qf, p1, 0, 0, 0); }
; }
; __device__ __forceinline__ void attn_unit(const bf16_t* __restrict__ Qb, const bf16_t* __restrict__ Kn, const bf16_t* __restrict__ Vh, const bf16_t* __restrict__ Kr,
;                                           bf16_t* GO, int seq, char* lds, const int tid) {
;     ...
;     const int bp = bc == 0 ? 2 : bc - 1, bn = bc == 2 ? 0 : bc + 1;
;     SBAR(); qkt(pB0, pB1, K_lds + bc * SHM_K, qr, qrl, r32, hi);
;     finishSM(pA0, pA1, alA, l_reg, pa0, pa1, pa2, pa3); SBAR();
;     SWRITE(bn, 0); SLOAD(0, (j + 2) * KVBLK); SBAR();
.Lattn_steady:
	s_sub_i32 s30, s76, 1
	s_cmp_eq_u32 s76, 0
	s_cselect_b32 s30, 2, s30
	s_add_i32 s18, s76, 1
	s_cmp_lg_u32 s76, 2
	s_cselect_b32 s18, s18, 0
	v_exp_f32_e32 v225, v225
	v_exp_f32_e32 v228, v228
	v_exp_f32_e32 v226, v226
	v_add_f32_e32 v211, v225, v228
	s_waitcnt lgkmcnt(2)
	v_mfma_f32_32x32x16_bf16 v[80:95], v[232:235], v[124:127], 0
	ds_read_b128 v[232:235], v206 offset:36864
	v_exp_f32_e32 v229, v229
	v_add_f32_e32 v211, v226, v211
	v_exp_f32_e32 v227, v227
	v_add_f32_e32 v211, v229, v211
	v_mfma_f32_32x32x16_bf16 v[64:79], v[236:239], v[124:127], 0
	ds_read_b128 v[236:239], v206 offset:49152
	v_exp_f32_e32 v230, v230
	v_add_f32_e32 v211, v227, v211
	v_exp_f32_e32 v223, v223
	v_add_f32_e32 v211, v230, v211
	s_waitcnt lgkmcnt(2)
	v_mfma_f32_32x32x16_bf16 v[80:95], v[240:243], v[120:123], v[80:95]
	ds_read_b128 v[240:243], v208 offset:36864
	v_exp_f32_e32 v224, v224
	v_add_f32_e32 v211, v223, v211
	v_exp_f32_e32 v219, v219
	v_add_f32_e32 v211, v224, v211
	v_mfma_f32_32x32x16_bf16 v[64:79], v[248:251], v[120:123], v[64:79]
	ds_read_b128 v[248:251], v208 offset:49152
	v_exp_f32_e32 v221, v221
	v_add_f32_e32 v211, v219, v211
	v_exp_f32_e32 v220, v220
	v_add_f32_e32 v211, v221, v211
	s_waitcnt lgkmcnt(2)
	v_mfma_f32_32x32x16_bf16 v[80:95], v[232:235], v[116:119], v[80:95]
	ds_read_b128 v[232:235], v207 offset:36864
	v_exp_f32_e32 v222, v222
	v_add_f32_e32 v211, v220, v211
	v_exp_f32_e32 v215, v215
	v_add_f32_e32 v211, v222, v211
	v_mfma_f32_32x32x16_bf16 v[64:79], v[236:239], v[116:119], v[64:79]
	ds_read_b128 v[236:239], v207 offset:49152
	v_exp_f32_e32 v217, v217
	v_add_f32_e32 v211, v215, v211
	v_exp_f32_e32 v216, v216
	v_add_f32_e32 v211, v217, v211
	s_waitcnt lgkmcnt(2)
	v_mfma_f32_32x32x16_bf16 v[80:95], v[240:243], v[112:115], v[80:95]
	ds_read_b128 v[240:243], v204 offset:36864
	v_exp_f32_e32 v218, v218
	v_add_f32_e32 v211, v216, v211
	v_exp_f32_e32 v162, v162
	v_add_f32_e32 v211, v218, v211
	v_mfma_f32_32x32x16_bf16 v[64:79], v[248:251], v[112:115], v[64:79]
	ds_read_b128 v[248:251], v204 offset:49152
	v_exp_f32_e32 v163, v163
	v_exp_f32_e32 v160, v160
	v_exp_f32_e32 v161, v161
	s_waitcnt lgkmcnt(2)
	v_mfma_f32_32x32x16_bf16 v[80:95], v[232:235], v[108:111], v[80:95]
	ds_read_b128 v[232:235], v203 offset:36864
	v_exp_f32_e32 v158, v158
	v_exp_f32_e32 v159, v159
	v_exp_f32_e32 v156, v156
	v_mfma_f32_32x32x16_bf16 v[64:79], v[236:239], v[108:111], v[64:79]
	ds_read_b128 v[236:239], v203 offset:49152
	v_exp_f32_e32 v157, v157
	v_exp_f32_e32 v154, v154
	v_exp_f32_e32 v155, v155
	s_waitcnt lgkmcnt(2)
	v_mfma_f32_32x32x16_bf16 v[80:95], v[240:243], v[104:107], v[80:95]
	ds_read_b128 v[240:243], v200 offset:36864
	v_exp_f32_e32 v152, v152
	v_exp_f32_e32 v153, v153
	v_exp_f32_e32 v150, v150
	v_mfma_f32_32x32x16_bf16 v[64:79], v[248:251], v[104:107], v[64:79]
	ds_read_b128 v[248:251], v200 offset:49152
	v_exp_f32_e32 v151, v151
	v_exp_f32_e32 v148, v148
	v_exp_f32_e32 v149, v149
	s_waitcnt lgkmcnt(2)
	v_mfma_f32_32x32x16_bf16 v[80:95], v[232:235], v[100:103], v[80:95]
	ds_read_b128 v[232:235], v191 offset:36864
	v_add_f32_e32 v212, v162, v163
	v_add_f32_e32 v212, v160, v212
	v_add_f32_e32 v212, v161, v212
	v_add_f32_e32 v212, v158, v212
	v_add_f32_e32 v212, v159, v212
	v_add_f32_e32 v212, v156, v212
	v_mfma_f32_32x32x16_bf16 v[64:79], v[236:239], v[100:103], v[64:79]
	ds_read_b128 v[236:239], v202 offset:49152
	v_add_f32_e32 v212, v157, v212
	v_add_f32_e32 v212, v154, v212
	v_add_f32_e32 v212, v155, v212
	v_add_f32_e32 v212, v152, v212
	v_add_f32_e32 v212, v153, v212
	v_add_f32_e32 v212, v150, v212
	s_waitcnt lgkmcnt(2)
	v_mfma_f32_32x32x16_bf16 v[80:95], v[240:243], v[96:99], v[80:95]
	ds_read_b128 v[240:243], v182
	v_add_f32_e32 v212, v151, v212
	v_add_f32_e32 v212, v148, v212
	v_add_f32_e32 v212, v149, v212
	v_add_f32_e32 v211, v211, v212
	v_mov_b32_e32 v212, v211
	s_lshl_b32 s19, s18, 14
	v_add_u32_e32 v231, s19, v183
	s_waitcnt vmcnt(0)
	v_mfma_f32_32x32x16_bf16 v[64:79], v[248:251], v[96:99], v[64:79]
	ds_read_b128 v[248:251], v198 offset:36864
	ds_write_b128 v231, v[140:143]
	v_add_u32_e32 v140, s19, v184
	ds_write_b128 v140, v[144:147]
	ds_write_b128 v185, v[136:139] offset:12288
	ds_write_b128 v185, v[132:135] offset:24576
	s_mov_b32 s18, 0xfffa0000
	ds_write_b128 v186, v[128:131] offset:12288
	v_add_co_u32_e32 v128, vcc, s18, v168
	s_mov_b32 s18, 0xfffc0000
	s_nop 0
	s_waitcnt lgkmcnt(6)
; __device__ __forceinline__ void finishSM(f32x16& p0, f32x16& p1, float alpha, float& l_reg, bf16x8& pa0, bf16x8& pa1, bf16x8& pa2, bf16x8& pa3) {
;     ...
;   PK4(p0, 0, pa0); PK4(p0, 8, pa1); PK4(p1, 0, pa2); PK4(p1, 8, pa3);
;     ...
; }
; __device__ __forceinline__ void qkt(f32x16& p0, f32x16& p1, const char* Ks, const bf16x8* qr, const char* qrl, int r32, int hi) {
;   p0 = f32x16{}; p1 = f32x16{};
; #pragma unroll
;   for (int d0 = 0; d0 < 8; ++d0) { int cb = (d0 * 16 + hi * 8) * 2;
;     bf16x8 b0 = *reinterpret_cast<const bf16x8*>(Ks + KSWZ(r32, cb));
;     bf16x8 b1 = *reinterpret_cast<const bf16x8*>(Ks + KSWZ(32 + r32, cb));
;     p0 = __builtin_amdgcn_mfma_f32_32x32x16_bf16(b0, qr[d0], p0, 0, 0, 0);
;     p1 = __builtin_amdgcn_mfma_f32_32x32x16_bf16(b1, qr[d0], p1, 0, 0, 0); }
; #pragma unroll
;   for (int d0 = 8; d0 < 12; ++d0) { int cb = (d0 * 16 + hi * 8) * 2;
;     bf16x8 b0 = *reinterpret_cast<const bf16x8*>(Ks + KSWZ(r32, cb));
;     bf16x8 b1 = *reinterpret_cast<const bf16x8*>(Ks + KSWZ(32 + r32, cb));
;     bf16x8 qf = *reinterpret_cast<const bf16x8*>(qrl + (((2 * (d0 - 8) + hi) ^ ((r32 >> 1) & 7)) << 4));
;     p0 = __builtin_amdgcn_mfma_f32_32x32x16_bf16(b0, qf, p0, 0, 0, 0);
;     p1 = __builtin_amdgcn_mfma_f32_32x32x16_bf16(b1, qf, p1, 0, 0, 0); }
; }
; __device__ __forceinline__ int v_st(int k, int c) { const int kk = (k & ~0xC) | ((k & 4) << 1) | ((k & 8) >> 1); return ((kk >> 3) * 4 + (c >> 5)) * 512 + ((kk & 7) * 32 + (c & 31)) * 2; }
; __device__ __forceinline__ int v_rd_base(int lane) { return ((lane & 3) << 3) | (((lane >> 2) & 3) << 6) | (((lane >> 4) & 1) << 5) | (((lane >> 5) & 1) << 8); }
; template <int OFF> __device__ __forceinline__ s16x4 tr_read(int vb) {
;   s16x4 r; asm volatile("ds_read_b64_tr_b16 %0, %1 offset:%2" : "=&v"(r) : "v"(vb), "i"(OFF) : "memory"); return r;
; }
; template <int D0> __device__ __forceinline__ void pv_one(f32x16& od, int vb, bf16x8 pa0, bf16x8 pa1, bf16x8 pa2, bf16x8 pa3) {
;   const s16x4 l0 = tr_read<v_rd_off(D0, 0, 0)>(vb), h0 = tr_read<v_rd_off(D0, 0, 1)>(vb), l1 = tr_read<v_rd_off(D0, 1, 0)>(vb), h1 = tr_read<v_rd_off(D0, 1, 1)>(vb);
;   const s16x4 l2 = tr_read<v_rd_off(D0, 2, 0)>(vb), h2 = tr_read<v_rd_off(D0, 2, 1)>(vb), l3 = tr_read<v_rd_off(D0, 3, 0)>(vb), h3 = tr_read<v_rd_off(D0, 3, 1)>(vb);
;   asm volatile("s_waitcnt lgkmcnt(0)" ::: "memory"); SBAR();
	v_mfma_f32_32x32x16_bf16 v[80:95], v[232:235], v[240:243], v[80:95]
	ds_read_b128 v[232:235], v201 offset:49152
	v_addc_co_u32_e32 v129, vcc, -1, v169, vcc
	v_add_co_u32_e32 v130, vcc, s18, v168
	s_movk_i32 s18, 0xe000
	s_nop 0
	v_addc_co_u32_e32 v131, vcc, -1, v169, vcc
	global_load_dwordx4 v[140:143], v[128:129], off
	global_load_dwordx4 v[136:139], v[128:129], off offset:-256
	global_load_dwordx4 v[144:147], v[130:131], off
	v_mfma_f32_32x32x16_bf16 v[64:79], v[236:239], v[240:243], v[64:79]
	ds_read_b128 v[236:239], v181
	ds_read_b128 v[240:243], v187 offset:36864
	global_load_dwordx4 v[132:135], v[130:131], off offset:-256
	v_add_co_u32_e32 v128, vcc, s18, v166
	s_nop 1
	v_addc_co_u32_e32 v129, vcc, -1, v167, vcc
	global_load_dwordx4 v[128:131], v[128:129], off
	v_cvt_pk_bf16_f32 v158, v158, v159
	v_cvt_pk_bf16_f32 v159, v156, v157
	s_waitcnt lgkmcnt(1)
	v_mfma_f32_32x32x16_bf16 v[80:95], v[248:251], v[236:239], v[80:95]
	ds_read_b128 v[248:251], v189 offset:49152
	v_permlane32_swap_b32_e32 v211, v212
	v_cvt_pk_bf16_f32 v156, v162, v163
	v_cvt_pk_bf16_f32 v157, v160, v161
	v_cvt_pk_bf16_f32 v160, v154, v155
	v_cvt_pk_bf16_f32 v161, v152, v153
	v_cvt_pk_bf16_f32 v162, v150, v151
	v_mfma_f32_32x32x16_bf16 v[64:79], v[232:235], v[236:239], v[64:79]
	ds_read_b128 v[232:235], v179
	ds_read_b128 v[236:239], v188 offset:36864
	v_cvt_pk_bf16_f32 v163, v148, v149
	v_add_f32_e32 v211, v211, v212
	v_cvt_pk_bf16_f32 v148, v225, v228
	v_cvt_pk_bf16_f32 v149, v226, v229
	v_cvt_pk_bf16_f32 v150, v227, v230
	v_cvt_pk_bf16_f32 v151, v223, v224
	s_waitcnt lgkmcnt(1)
	v_mfma_f32_32x32x16_bf16 v[80:95], v[240:243], v[232:235], v[80:95]
	ds_read_b128 v[240:243], v190 offset:49152
	v_cvt_pk_bf16_f32 v152, v219, v221
	v_cvt_pk_bf16_f32 v153, v220, v222
	v_cvt_pk_bf16_f32 v154, v215, v217
	v_cvt_pk_bf16_f32 v155, v216, v218
	v_fma_f32 v176, v209, v176, v211
	v_mfma_f32_32x32x16_bf16 v[64:79], v[248:251], v[232:235], v[64:79]
	ds_read_b128 v[248:251], v177
	s_waitcnt lgkmcnt(0)
	v_mfma_f32_32x32x16_bf16 v[80:95], v[236:239], v[248:251], v[80:95]
	v_mfma_f32_32x32x16_bf16 v[64:79], v[240:243], v[248:251], v[64:79]
	s_lshl_b32 s31, s30, 14
	v_add_u32_e32 v180, s31, v178
	ds_read_b64_tr_b16 v[232:233], v180 offset:0
	ds_read_b64_tr_b16 v[234:235], v180 offset:2048
	ds_read_b64_tr_b16 v[236:237], v180 offset:512
	ds_read_b64_tr_b16 v[238:239], v180 offset:2560
	ds_read_b64_tr_b16 v[240:241], v180 offset:1024
	ds_read_b64_tr_b16 v[242:243], v180 offset:3072
	ds_read_b64_tr_b16 v[248:249], v180 offset:1536
	ds_read_b64_tr_b16 v[250:251], v180 offset:3584
	s_nop 3
	v_max3_f32 v194, v80, v81, v82
	v_max3_f32 v195, v64, v65, v66
	v_max3_f32 v194, v194, v83, v84
	v_max3_f32 v195, v195, v67, v68
	s_waitcnt lgkmcnt(4)
	v_mfma_f32_32x32x16_bf16 v[32:47], v[148:151], v[232:235], v[32:47]
	ds_read_b64_tr_b16 v[232:233], v180 offset:4096
	ds_read_b64_tr_b16 v[234:235], v180 offset:6144
	v_max3_f32 v194, v194, v85, v86
	v_max3_f32 v195, v195, v69, v70
	v_max3_f32 v194, v194, v87, v88
	v_max3_f32 v195, v195, v71, v72
	v_mfma_f32_32x32x16_bf16 v[48:63], v[148:151], v[236:239], v[48:63]
	ds_read_b64_tr_b16 v[236:237], v180 offset:4608
	ds_read_b64_tr_b16 v[238:239], v180 offset:6656
	v_max3_f32 v194, v194, v89, v90
	v_max3_f32 v195, v195, v73, v74
	v_max3_f32 v194, v194, v91, v92
	v_max3_f32 v195, v195, v75, v76
	s_waitcnt lgkmcnt(4)
	v_mfma_f32_32x32x16_bf16 v[16:31], v[148:151], v[240:243], v[16:31]
	ds_read_b64_tr_b16 v[240:241], v180 offset:5120
	ds_read_b64_tr_b16 v[242:243], v180 offset:7168
	v_max3_f32 v194, v194, v93, v94
	v_max3_f32 v195, v195, v77, v78
	v_max3_f32 v194, v194, v95, v195
	v_max_f32_e32 v194, v194, v79
	v_mfma_f32_32x32x16_bf16 v[0:15], v[148:151], v[248:251], v[0:15]
	ds_read_b64_tr_b16 v[248:249], v180 offset:5632
	ds_read_b64_tr_b16 v[250:251], v180 offset:7680
	v_mov_b32_e32 v195, v194
	s_nop 1
	v_permlane32_swap_b32_e32 v194, v195
	v_max_f32_e32 v194, v194, v195
	s_waitcnt lgkmcnt(4)
	v_mfma_f32_32x32x16_bf16 v[32:47], v[152:155], v[232:235], v[32:47]
	ds_read_b64_tr_b16 v[232:233], v180 offset:8192
	ds_read_b64_tr_b16 v[234:235], v180 offset:10240
	v_sub_f32_e32 v195, v194, v210
	v_cmp_ge_f32_e32 vcc, s15, v195
	v_mfma_f32_32x32x16_bf16 v[48:63], v[152:155], v[236:239], v[48:63]
	ds_read_b64_tr_b16 v[236:237], v180 offset:8704
	ds_read_b64_tr_b16 v[238:239], v180 offset:10752
	s_cmp_eq_u64 vcc, exec
	s_cselect_b64 s[40:41], -1, 0
	s_cbranch_scc1 .Lattn_fast1
	v_max_f32_e32 v194, v210, v194
	v_sub_f32_e32 v195, v210, v194
	v_mul_f32_e32 v195, 0x3dd53b94, v195
	v_exp_f32_e32 v214, v195
	v_mov_b32_e32 v210, v194
	s_branch .Lattn_join1

; #define SBAR() __builtin_amdgcn_sched_barrier(0)
; __device__ __forceinline__ void qkt(f32x16& p0, f32x16& p1, const char* Ks, const bf16x8* qr, const char* qrl, int r32, int hi) {
;   p0 = f32x16{}; p1 = f32x16{};
; #pragma unroll
;   for (int d0 = 0; d0 < 8; ++d0) { int cb = (d0 * 16 + hi * 8) * 2;
;     bf16x8 b0 = *reinterpret_cast<const bf16x8*>(Ks + KSWZ(r32, cb));
;     bf16x8 b1 = *reinterpret_cast<const bf16x8*>(Ks + KSWZ(32 + r32, cb));
;     p0 = __builtin_amdgcn_mfma_f32_32x32x16_bf16(b0, qr[d0], p0, 0, 0, 0);
;     p1 = __builtin_amdgcn_mfma_f32_32x32x16_bf16(b1, qr[d0], p1, 0, 0, 0); }
; #pragma unroll
;   for (int d0 = 8; d0 < 12; ++d0) { int cb = (d0 * 16 + hi * 8) * 2;
;     bf16x8 b0 = *reinterpret_cast<const bf16x8*>(Ks + KSWZ(r32, cb));
;     bf16x8 b1 = *reinterpret_cast<const bf16x8*>(Ks + KSWZ(32 + r32, cb));
;     bf16x8 qf = *reinterpret_cast<const bf16x8*>(qrl + (((2 * (d0 - 8) + hi) ^ ((r32 >> 1) & 7)) << 4));
;     p0 = __builtin_amdgcn_mfma_f32_32x32x16_bf16(b0, qf, p0, 0, 0, 0);
;     p1 = __builtin_amdgcn_mfma_f32_32x32x16_bf16(b1, qf, p1, 0, 0, 0); }
; }
; __device__ __forceinline__ void attn_unit(const bf16_t* __restrict__ Qb, const bf16_t* __restrict__ Kn, const bf16_t* __restrict__ Vh, const bf16_t* __restrict__ Kr,
;                                           bf16_t* GO, int seq, char* lds, const int tid) {
;     ...
;   for (int j = 1; j + 1 < NT; j += 2) {
;     const int bp = bc == 0 ? 2 : bc - 1, bn = bc == 2 ? 0 : bc + 1;
;     SBAR(); qkt(pB0, pB1, K_lds + bc * SHM_K, qr, qrl, r32, hi);
;     finishSM(pA0, pA1, alA, l_reg, pa0, pa1, pa2, pa3); SBAR();
;     SWRITE(bn, 0); SLOAD(0, (j + 2) * KVBLK); SBAR();
;     pv_d0(o, vb0 + bp * SHM_V, pa0, pa1, pa2, pa3); partialSM(pB0, pB1, m_reg, mnB, alB);
;     RESC(alB); LBAR();
;     SBAR(); qkt(pA0, pA1, K_lds + bn * SHM_K, qr, qrl, r32, hi);
;     finishSM(pB0, pB1, alB, l_reg, pa0, pa1, pa2, pa3); SBAR();
;     SWRITE(bp, 0); if (j + 3 < NT) SLOAD(0, (j + 3) * KVBLK); SBAR();
;     pv_d0(o, vb0 + bc * SHM_V, pa0, pa1, pa2, pa3); partialSM(pA0, pA1, m_reg, mnA, alA);
;     RESC(alA); LBAR();
;     bc = bp;
;   }
;   { const int bp = bc == 0 ? 2 : bc - 1;
;     SBAR(); qkt(pB0, pB1, K_lds + bc * SHM_K, qr, qrl, r32, hi);
;     finishSM(pA0, pA1, alA, l_reg, pa0, pa1, pa2, pa3); SBAR();
.Lattn_skip_rs2:
	s_movk_i32 s34, 0x6000
	s_mov_b64 s[18:19], 0x4000
	v_lshl_add_u64 v[166:167], v[166:167], 0, s[18:19]
	v_lshl_add_u64 v[168:169], v[168:169], 0, s[10:11]
	s_and_b64 vcc, exec, s[28:29]
	s_cbranch_vccnz .LBB0_1163
	s_mov_b32 s76, s30
	v_mov_b32_e32 v209, v213
	s_branch .Lattn_steady
.LBB0_1163:
	s_waitcnt lgkmcnt(0)
	v_add_u32_e32 v199, 0xffff7000, v199
	v_add_u32_e32 v205, 0xffff7000, v205
	v_add_u32_e32 v206, 0xffff7000, v206
	v_add_u32_e32 v208, 0xffff7000, v208
	v_add_u32_e32 v207, 0xffff7000, v207
	v_add_u32_e32 v204, 0xffff7000, v204
	v_add_u32_e32 v203, 0xffff7000, v203
	v_add_u32_e32 v200, 0xffff7000, v200
	v_add_u32_e32 v191, 0xffff7000, v191
	v_add_u32_e32 v198, 0xffff7000, v198
	v_add_u32_e32 v187, 0xffff7000, v187
	v_add_u32_e32 v188, 0xffff7000, v188
	v_add_u32_e32 v202, 0xffff7000, v202
	v_add_u32_e32 v201, 0xffff7000, v201
	v_add_u32_e32 v189, 0xffff7000, v189
	v_add_u32_e32 v190, 0xffff7000, v190
	v_add_u32_e32 v185, 0xffff7000, v185
	v_add_u32_e32 v186, 0xffff7000, v186
	v_exp_f32_e32 v225, v225
	v_exp_f32_e32 v228, v228
	v_exp_f32_e32 v226, v226
	v_exp_f32_e32 v229, v229
	v_exp_f32_e32 v227, v227
	v_exp_f32_e32 v230, v230
	v_exp_f32_e32 v223, v223
	v_exp_f32_e32 v224, v224
	v_exp_f32_e32 v219, v219
	v_exp_f32_e32 v221, v221
	v_exp_f32_e32 v220, v220
	v_exp_f32_e32 v222, v222
	v_exp_f32_e32 v215, v215
	v_exp_f32_e32 v217, v217
	v_exp_f32_e32 v216, v216
	v_exp_f32_e32 v218, v218
	s_nop 0
	v_add_u32_e32 v68, s34, v199
	ds_read_b128 v[64:67], v68 offset:49152
	ds_read_b128 v[68:71], v68 offset:61440
	s_waitcnt vmcnt(0)
	v_add_u32_e32 v128, s34, v205
	s_waitcnt lgkmcnt(1)
	v_mfma_f32_32x32x16_bf16 v[80:95], v[64:67], v[124:127], 0
	s_waitcnt lgkmcnt(0)
	v_mfma_f32_32x32x16_bf16 v[64:79], v[68:71], v[124:127], 0
	ds_read_b128 v[124:127], v128 offset:49152
	ds_read_b128 v[128:131], v128 offset:61440
	s_waitcnt lgkmcnt(1)
	v_mfma_f32_32x32x16_bf16 v[80:95], v[124:127], v[120:123], v[80:95]
	v_add_u32_e32 v124, s34, v206
	s_waitcnt lgkmcnt(0)
	v_mfma_f32_32x32x16_bf16 v[64:79], v[128:131], v[120:123], v[64:79]
	ds_read_b128 v[120:123], v124 offset:49152
	ds_read_b128 v[124:127], v124 offset:61440
	s_waitcnt lgkmcnt(1)
	v_mfma_f32_32x32x16_bf16 v[80:95], v[120:123], v[116:119], v[80:95]
	v_add_u32_e32 v120, s34, v208
	s_waitcnt lgkmcnt(0)
	v_mfma_f32_32x32x16_bf16 v[64:79], v[124:127], v[116:119], v[64:79]
	ds_read_b128 v[116:119], v120 offset:49152
	ds_read_b128 v[120:123], v120 offset:61440
	s_waitcnt lgkmcnt(1)
	v_mfma_f32_32x32x16_bf16 v[80:95], v[116:119], v[112:115], v[80:95]
	v_add_u32_e32 v116, s34, v207
	s_waitcnt lgkmcnt(0)
	v_mfma_f32_32x32x16_bf16 v[64:79], v[120:123], v[112:115], v[64:79]
	ds_read_b128 v[112:115], v116 offset:49152
	ds_read_b128 v[116:119], v116 offset:61440
	v_exp_f32_e32 v120, v148
	v_exp_f32_e32 v121, v149
	s_waitcnt lgkmcnt(1)
	v_mfma_f32_32x32x16_bf16 v[80:95], v[112:115], v[108:111], v[80:95]
	v_add_u32_e32 v112, s34, v204
	s_waitcnt lgkmcnt(0)
	v_mfma_f32_32x32x16_bf16 v[64:79], v[116:119], v[108:111], v[64:79]
	ds_read_b128 v[108:111], v112 offset:49152
	ds_read_b128 v[112:115], v112 offset:61440
	v_exp_f32_e32 v116, v152
	v_exp_f32_e32 v117, v153
	v_exp_f32_e32 v118, v150
	v_exp_f32_e32 v119, v151
	s_waitcnt lgkmcnt(1)
	v_mfma_f32_32x32x16_bf16 v[80:95], v[108:111], v[104:107], v[80:95]
	v_add_u32_e32 v108, s34, v203
	s_waitcnt lgkmcnt(0)
	v_mfma_f32_32x32x16_bf16 v[64:79], v[112:115], v[104:107], v[64:79]
	ds_read_b128 v[104:107], v108 offset:49152
	ds_read_b128 v[108:111], v108 offset:61440
	v_exp_f32_e32 v112, v156
	v_exp_f32_e32 v113, v157
	v_exp_f32_e32 v114, v154
	v_exp_f32_e32 v115, v155
	s_waitcnt lgkmcnt(1)
	v_mfma_f32_32x32x16_bf16 v[80:95], v[104:107], v[100:103], v[80:95]
	v_add_u32_e32 v104, s34, v200
	s_waitcnt lgkmcnt(0)
	v_mfma_f32_32x32x16_bf16 v[64:79], v[108:111], v[100:103], v[64:79]
	ds_read_b128 v[100:103], v104 offset:49152
	ds_read_b128 v[104:107], v104 offset:61440
	v_exp_f32_e32 v108, v160
	v_exp_f32_e32 v109, v161
	v_exp_f32_e32 v110, v158
	v_exp_f32_e32 v111, v159
	s_waitcnt lgkmcnt(1)
	v_mfma_f32_32x32x16_bf16 v[80:95], v[100:103], v[96:99], v[80:95]
	v_add_u32_e32 v100, s34, v202
	s_waitcnt lgkmcnt(0)
	v_mfma_f32_32x32x16_bf16 v[64:79], v[104:107], v[96:99], v[64:79]
	v_add_u32_e32 v96, s34, v191
	ds_read_b128 v[96:99], v96 offset:49152
	ds_read_b128 v[100:103], v100 offset:61440
	ds_read_b128 v[104:107], v182
	s_waitcnt lgkmcnt(0)
	v_mfma_f32_32x32x16_bf16 v[80:95], v[96:99], v[104:107], v[80:95]
	v_add_u32_e32 v96, s34, v198
	ds_read_b128 v[96:99], v96 offset:49152
	v_mfma_f32_32x32x16_bf16 v[64:79], v[100:103], v[104:107], v[64:79]
	v_add_u32_e32 v100, s34, v201
	ds_read_b128 v[100:103], v100 offset:61440
	ds_read_b128 v[104:107], v181
	s_waitcnt lgkmcnt(0)
	v_mfma_f32_32x32x16_bf16 v[80:95], v[96:99], v[104:107], v[80:95]
	v_add_u32_e32 v96, s34, v187
	ds_read_b128 v[96:99], v96 offset:49152
	v_mfma_f32_32x32x16_bf16 v[64:79], v[100:103], v[104:107], v[64:79]
	v_add_u32_e32 v100, s34, v189
	ds_read_b128 v[100:103], v100 offset:61440
	ds_read_b128 v[104:107], v179
	s_waitcnt lgkmcnt(0)
	v_mfma_f32_32x32x16_bf16 v[80:95], v[96:99], v[104:107], v[80:95]
	v_add_u32_e32 v96, s34, v188
	ds_read_b128 v[96:99], v96 offset:49152
	v_mfma_f32_32x32x16_bf16 v[64:79], v[100:103], v[104:107], v[64:79]
	v_add_u32_e32 v100, s34, v190
	ds_read_b128 v[100:103], v100 offset:61440
	ds_read_b128 v[104:107], v177
	s_waitcnt lgkmcnt(0)
; #define SBAR() __builtin_amdgcn_sched_barrier(0)
; __device__ __forceinline__ void finishSM(f32x16& p0, f32x16& p1, float alpha, float& l_reg, bf16x8& pa0, bf16x8& pa1, bf16x8& pa2, bf16x8& pa3) {
; #pragma unroll
;   for (int r = 0; r < 16; ++r) p1[r] = __builtin_amdgcn_exp2f(p1[r]);
;   float ps = 0;
; #pragma unroll
;   for (int r = 0; r < 16; ++r) ps += p0[r];
; #pragma unroll
;   for (int r = 0; r < 16; ++r) ps += p1[r];
;   { auto rr = __builtin_amdgcn_permlane32_swap(__float_as_uint(ps), __float_as_uint(ps), false, false);
;     ps = __uint_as_float(rr[0]) + __uint_as_float(rr[1]); }
;   l_reg = l_reg * alpha + ps;
;     ...
;   PK4(p0, 0, pa0); PK4(p0, 8, pa1); PK4(p1, 0, pa2); PK4(p1, 8, pa3);
;     ...
; }
; template <int D0> __device__ __forceinline__ void pv_one(f32x16& od, int vb, bf16x8 pa0, bf16x8 pa1, bf16x8 pa2, bf16x8 pa3) {
;   const s16x4 l0 = tr_read<v_rd_off(D0, 0, 0)>(vb), h0 = tr_read<v_rd_off(D0, 0, 1)>(vb), l1 = tr_read<v_rd_off(D0, 1, 0)>(vb), h1 = tr_read<v_rd_off(D0, 1, 1)>(vb);
;   const s16x4 l2 = tr_read<v_rd_off(D0, 2, 0)>(vb), h2 = tr_read<v_rd_off(D0, 2, 1)>(vb), l3 = tr_read<v_rd_off(D0, 3, 0)>(vb), h3 = tr_read<v_rd_off(D0, 3, 1)>(vb);
;   asm volatile("s_waitcnt lgkmcnt(0)" ::: "memory"); SBAR();
;     ...
;   od = __builtin_amdgcn_mfma_f32_32x32x16_bf16(pa0, PK(l0, h0), od, 0, 0, 0);
;   od = __builtin_amdgcn_mfma_f32_32x32x16_bf16(pa1, PK(l1, h1), od, 0, 0, 0);
;   od = __builtin_amdgcn_mfma_f32_32x32x16_bf16(pa2, PK(l2, h2), od, 0, 0, 0);
;   od = __builtin_amdgcn_mfma_f32_32x32x16_bf16(pa3, PK(l3, h3), od, 0, 0, 0);
;     ...
; }
; __device__ __forceinline__ void pv_d0(f32x16* o, int vb, bf16x8 pa0, bf16x8 pa1, bf16x8 pa2, bf16x8 pa3) {
;   pv_one<0>(o[0], vb, pa0, pa1, pa2, pa3); pv_one<1>(o[1], vb, pa0, pa1, pa2, pa3); pv_one<2>(o[2], vb, pa0, pa1, pa2, pa3); pv_one<3>(o[3], vb, pa0, pa1, pa2, pa3);
	v_mfma_f32_32x32x16_bf16 v[80:95], v[96:99], v[104:107], v[80:95]
	v_add_f32_e32 v96, 0, v225
	v_add_f32_e32 v96, v228, v96
	v_add_f32_e32 v96, v226, v96
	v_add_f32_e32 v96, v229, v96
	v_add_f32_e32 v96, v227, v96
	v_add_f32_e32 v96, v230, v96
	v_add_f32_e32 v96, v223, v96
	v_add_f32_e32 v96, v224, v96
	v_add_f32_e32 v96, v219, v96
	v_add_f32_e32 v96, v221, v96
	v_add_f32_e32 v96, v220, v96
	v_add_f32_e32 v96, v222, v96
	v_mfma_f32_32x32x16_bf16 v[64:79], v[100:103], v[104:107], v[64:79]
	v_exp_f32_e32 v106, v162
	v_add_f32_e32 v96, v215, v96
	v_exp_f32_e32 v107, v163
	v_add_f32_e32 v96, v217, v96
	v_add_f32_e32 v96, v216, v96
	v_add_f32_e32 v96, v218, v96
	v_add_f32_e32 v96, v106, v96
	v_add_f32_e32 v96, v107, v96
	v_add_f32_e32 v96, v108, v96
	v_add_f32_e32 v96, v109, v96
	v_add_f32_e32 v96, v110, v96
	v_add_f32_e32 v96, v111, v96
	v_add_f32_e32 v96, v112, v96
	v_add_f32_e32 v96, v113, v96
	v_add_f32_e32 v96, v114, v96
	v_add_f32_e32 v96, v115, v96
	v_add_f32_e32 v96, v116, v96
	v_add_f32_e32 v96, v117, v96
	v_add_f32_e32 v96, v118, v96
	v_add_f32_e32 v96, v119, v96
	v_add_f32_e32 v96, v120, v96
	v_add_f32_e32 v100, v121, v96
	v_mov_b32_e32 v101, v100
	v_cvt_pk_bf16_f32 v96, v225, v228
	v_cvt_pk_bf16_f32 v97, v226, v229
	v_cvt_pk_bf16_f32 v98, v227, v230
	v_cvt_pk_bf16_f32 v99, v223, v224
	s_nop 1
	v_permlane32_swap_b32_e32 v100, v101
	v_cvt_pk_bf16_f32 v102, v219, v221
	v_cvt_pk_bf16_f32 v103, v220, v222
	v_cvt_pk_bf16_f32 v104, v215, v217
	v_cvt_pk_bf16_f32 v105, v216, v218
	v_cvt_pk_bf16_f32 v106, v106, v107
	v_cvt_pk_bf16_f32 v107, v108, v109
	v_cvt_pk_bf16_f32 v108, v110, v111
	v_cvt_pk_bf16_f32 v109, v112, v113
	v_cvt_pk_bf16_f32 v110, v114, v115
	v_cvt_pk_bf16_f32 v111, v116, v117
	v_cvt_pk_bf16_f32 v112, v118, v119
	v_cvt_pk_bf16_f32 v113, v120, v121
	s_nop 0
	s_addk_i32 s31, 0xc000
	s_cmp_lg_u32 s30, 0
	s_cselect_b32 s18, s31, 0x8000
	v_add_u32_e32 v130, s18, v178
	ds_read_b64_tr_b16 v[114:115], v130 offset:0
	ds_read_b64_tr_b16 v[116:117], v130 offset:0x800
	ds_read_b64_tr_b16 v[118:119], v130 offset:0x1000
	ds_read_b64_tr_b16 v[120:121], v130 offset:0x1800
	ds_read_b64_tr_b16 v[122:123], v130 offset:0x2000
	ds_read_b64_tr_b16 v[124:125], v130 offset:0x2800
	ds_read_b64_tr_b16 v[126:127], v130 offset:0x3000
	ds_read_b64_tr_b16 v[128:129], v130 offset:0x3800
	s_waitcnt lgkmcnt(0)
	s_nop 0
	v_mfma_f32_32x32x16_bf16 v[32:47], v[96:99], v[114:117], v[32:47]
	ds_read_b64_tr_b16 v[114:115], v130 offset:0x200
	ds_read_b64_tr_b16 v[116:117], v130 offset:0xa00
	v_mfma_f32_32x32x16_bf16 v[32:47], v[102:105], v[118:121], v[32:47]
	ds_read_b64_tr_b16 v[118:119], v130 offset:0x1200
	ds_read_b64_tr_b16 v[120:121], v130 offset:0x1a00
	v_mfma_f32_32x32x16_bf16 v[32:47], v[106:109], v[122:125], v[32:47]
	ds_read_b64_tr_b16 v[122:123], v130 offset:0x2200
	ds_read_b64_tr_b16 v[124:125], v130 offset:0x2a00
	v_mfma_f32_32x32x16_bf16 v[32:47], v[110:113], v[126:129], v[32:47]
	ds_read_b64_tr_b16 v[126:127], v130 offset:0x3200
	ds_read_b64_tr_b16 v[128:129], v130 offset:0x3a00
	s_waitcnt lgkmcnt(0)
	v_mfma_f32_32x32x16_bf16 v[48:63], v[96:99], v[114:117], v[48:63]
	ds_read_b64_tr_b16 v[114:115], v130 offset:0x400
	ds_read_b64_tr_b16 v[116:117], v130 offset:0xc00
	v_mfma_f32_32x32x16_bf16 v[48:63], v[102:105], v[118:121], v[48:63]
	ds_read_b64_tr_b16 v[118:119], v130 offset:0x1400
	ds_read_b64_tr_b16 v[120:121], v130 offset:0x1c00
	v_mfma_f32_32x32x16_bf16 v[48:63], v[106:109], v[122:125], v[48:63]
	ds_read_b64_tr_b16 v[122:123], v130 offset:0x2400
	ds_read_b64_tr_b16 v[124:125], v130 offset:0x2c00
	v_mfma_f32_32x32x16_bf16 v[48:63], v[110:113], v[126:129], v[48:63]
	ds_read_b64_tr_b16 v[126:127], v130 offset:0x3400
	ds_read_b64_tr_b16 v[128:129], v130 offset:0x3c00
	s_waitcnt lgkmcnt(0)
	v_mfma_f32_32x32x16_bf16 v[16:31], v[96:99], v[114:117], v[16:31]
	ds_read_b64_tr_b16 v[114:115], v130 offset:0x600
	ds_read_b64_tr_b16 v[116:117], v130 offset:0xe00
	v_mfma_f32_32x32x16_bf16 v[16:31], v[102:105], v[118:121], v[16:31]
	ds_read_b64_tr_b16 v[118:119], v130 offset:0x1600
	ds_read_b64_tr_b16 v[120:121], v130 offset:0x1e00
	v_mfma_f32_32x32x16_bf16 v[16:31], v[106:109], v[122:125], v[16:31]
	ds_read_b64_tr_b16 v[122:123], v130 offset:0x2600
	ds_read_b64_tr_b16 v[124:125], v130 offset:0x2e00
	v_mfma_f32_32x32x16_bf16 v[16:31], v[110:113], v[126:129], v[16:31]
	ds_read_b64_tr_b16 v[126:127], v130 offset:0x3600
	ds_read_b64_tr_b16 v[128:129], v130 offset:0x3e00
	s_waitcnt lgkmcnt(0)
	v_mfma_f32_32x32x16_bf16 v[0:15], v[96:99], v[114:117], v[0:15]
	v_max_f32_e32 v96, v81, v81
	v_max_f32_e32 v97, v80, v80
	v_max_f32_e32 v96, v97, v96
	v_max3_f32 v96, v96, v82, v83
	v_max3_f32 v96, v96, v84, v85
	v_max3_f32 v96, v96, v86, v87
	v_max3_f32 v96, v96, v88, v89
	v_max3_f32 v96, v96, v90, v91
	v_max3_f32 v96, v96, v92, v93
	v_mfma_f32_32x32x16_bf16 v[0:15], v[102:105], v[118:121], v[0:15]
	v_max3_f32 v96, v96, v94, v95
	v_max3_f32 v96, v96, v64, v65
	v_max3_f32 v96, v96, v66, v67
	v_max3_f32 v96, v96, v68, v69
	v_max3_f32 v96, v96, v70, v71
	v_max3_f32 v96, v96, v72, v73
	v_max3_f32 v96, v96, v74, v75
	v_max3_f32 v96, v96, v76, v77
	v_mfma_f32_32x32x16_bf16 v[0:15], v[106:109], v[122:125], v[0:15]
	v_max3_f32 v96, v96, v78, v79
	v_mov_b32_e32 v97, v96
	s_nop 1
	v_permlane32_swap_b32_e32 v96, v97
	v_max_f32_e32 v97, v97, v97
	v_max_f32_e32 v96, v96, v96
	v_max_f32_e32 v96, v96, v97
	v_sub_f32_e32 v97, v96, v210
	v_cmp_ge_f32_e32 vcc, s15, v97
	v_max_f32_e32 v97, v210, v210
	v_max_f32_e32 v97, v97, v96
	v_mfma_f32_32x32x16_bf16 v[0:15], v[110:113], v[126:129], v[0:15]
	v_sub_f32_e32 v96, v210, v97
	v_mul_f32_e32 v96, 0x3dd53b94, v96
	v_exp_f32_e32 v96, v96
	s_cmp_eq_u64 vcc, exec
	s_cselect_b64 s[40:41], -1, 0
	v_cndmask_b32_e64 v96, v96, 1.0, s[40:41]
	v_cmp_gt_f32_e32 vcc, 1.0, v96
	s_cbranch_vccz .LBB0_1167
	s_and_saveexec_b64 s[18:19], s[38:39]
	ds_write_b32 v175, v96 offset:128
	s_or_b64 exec, exec, s[18:19]
	s_waitcnt lgkmcnt(0)
	v_add_u32_e32 v98, v173, v164
	ds_read_b128 v[102:105], v98 offset:224
	ds_read_b128 v[106:109], v98 offset:192
	ds_read_b128 v[110:113], v98 offset:160
	ds_read_b128 v[114:117], v98 offset:128
	s_waitcnt lgkmcnt(3)
	v_pk_mul_f32 v[44:45], v[44:45], v[102:103]
	s_waitcnt lgkmcnt(2)
	v_pk_mul_f32 v[40:41], v[40:41], v[106:107]
	s_waitcnt lgkmcnt(1)
	v_pk_mul_f32 v[36:37], v[36:37], v[110:111]
	v_pk_mul_f32 v[46:47], v[46:47], v[104:105]
	v_pk_mul_f32 v[42:43], v[42:43], v[108:109]
	v_pk_mul_f32 v[38:39], v[38:39], v[112:113]
	s_waitcnt lgkmcnt(0)
	v_pk_mul_f32 v[34:35], v[34:35], v[116:117]
	v_pk_mul_f32 v[32:33], v[32:33], v[114:115]
	v_pk_mul_f32 v[60:61], v[60:61], v[102:103]
	v_pk_mul_f32 v[56:57], v[56:57], v[106:107]
	v_pk_mul_f32 v[52:53], v[52:53], v[110:111]
	v_pk_mul_f32 v[62:63], v[62:63], v[104:105]
	v_pk_mul_f32 v[58:59], v[58:59], v[108:109]
	v_pk_mul_f32 v[54:55], v[54:55], v[112:113]
	v_pk_mul_f32 v[50:51], v[50:51], v[116:117]
	v_pk_mul_f32 v[48:49], v[48:49], v[114:115]
	v_pk_mul_f32 v[28:29], v[28:29], v[102:103]
	v_pk_mul_f32 v[24:25], v[24:25], v[106:107]
	v_pk_mul_f32 v[20:21], v[20:21], v[110:111]
	v_pk_mul_f32 v[30:31], v[30:31], v[104:105]
	v_pk_mul_f32 v[26:27], v[26:27], v[108:109]
	v_pk_mul_f32 v[22:23], v[22:23], v[112:113]
	v_pk_mul_f32 v[18:19], v[18:19], v[116:117]
	v_pk_mul_f32 v[16:17], v[16:17], v[114:115]
	v_pk_mul_f32 v[12:13], v[12:13], v[102:103]
	v_pk_mul_f32 v[8:9], v[8:9], v[106:107]
	v_pk_mul_f32 v[4:5], v[4:5], v[110:111]
	v_pk_mul_f32 v[14:15], v[14:15], v[104:105]
	v_pk_mul_f32 v[10:11], v[10:11], v[108:109]
	v_pk_mul_f32 v[6:7], v[6:7], v[112:113]
	v_pk_mul_f32 v[2:3], v[2:3], v[116:117]
	v_pk_mul_f32 v[0:1], v[0:1], v[114:115]
